# code placement: the five GEMM K-loop heads aligned to 64 bytes (.p2align 6, s_nop fill executed once per unit)
# baseline (speedup 1.0000x reference)
;     __device__ __forceinline__ bool next(int i, Unit& u) const { if (!base.next(i >> 1, u)) return false; if (i & 1) { u.pm += 64; u.pn += 8; } return true; }
; #define PG8_STAGE(bufoff, gbase, voff) do { _Pragma("unroll") for (int _i = 0; _i < 2; ++_i) \
;         __builtin_amdgcn_global_load_lds((const unsigned*)((const char*)(gbase) + (voff)[_i]), (PG8_LAS unsigned*)(lds + (bufoff) + ldsw + _i * 8192), 16, 0, 0); } while (0)
; #define PG8_LDA(dst, b, h) do { _Pragma("unroll") for (int m = 0; m < 4; ++m) _Pragma("unroll") for (int k = 0; k < 2; ++k) dst[m][k] = *(const PG8_LAS bf16x8*)(lds + PG8_SA(b, h) + aoff + m * 2048 + k * 1024); } while (0)
; #define PG8_LDB(dst, b, h) do { _Pragma("unroll") for (int n = 0; n < 2; ++n) _Pragma("unroll") for (int k = 0; k < 2; ++k) dst[n][k] = *(const PG8_LAS bf16x8*)(lds + PG8_SB(b, h) + boff + n * 2048 + k * 1024); } while (0)
; #define PG8_WAIT_V(n) asm volatile("s_waitcnt vmcnt(" #n ")" ::: "memory")
; #define PG8_WAIT_L(n) asm volatile("s_waitcnt lgkmcnt(" #n ")" ::: "memory")
; #define PG8_BAR __builtin_amdgcn_s_barrier()
; #define PG8_SCHED __builtin_amdgcn_sched_barrier(0)
; template <class Epi, class Sched, bool ALIGN_EPI = false, bool SP2 = false>
; __device__ __forceinline__ void gemm_phase(PG8_LAS unsigned char* lds, const Gemm g, const Sched& S, const Epi& E) {
;     ...
;         const bool has_next = S.next(ui + 1, nxt);
;         const char* nA = has_next ? (const char*)g.A + (size_t)nxt.pm * tstep : cA; const char* nB = has_next ? (const char*)g.Bt + (size_t)nxt.pn * tstep : cB;
;         for (int t = 0; t < nt; t += 2) {
;             const bool last = (t == nt - 2);
;             const char* a1 = cA + (size_t)(t + 1) * kstep;
;             const char* a2 = last ? nA : cA + (size_t)(t + 2) * kstep; const char* b2 = last ? nB : cB + (size_t)(t + 2) * kstep;
;             const char* a3 = a2 + kstep; const char* b3 = b2 + kstep;
;             if (last && has_next) S.a_ready(nxt);
;             if constexpr (SP2) {
;             PG8_LDB(B0, 0, 0); PG8_LDB(B1, 0, 1); PG8_SCHED; PG8_LDA(At, 0, 0); PG8_STAGE(PG8_SA(1, 1), a1 + hstep, voffA);
;             PG8_WAIT_V(8); PG8_WAIT_L(0); PG8_BAR; PG8_MMA(0, 0, At, B0); PG8_MMA(0, 1, At, B1); PG8_BAR; PG8_SCHED;
;             PG8_LDA(At, 0, 1); PG8_STAGE(PG8_SB(0, 0), b2, voffB); PG8_STAGE(PG8_SB(0, 1), b2 + hstep, voffB); PG8_STAGE(PG8_SA(0, 0), a2, voffA);
.LBB0_204:
	s_ashr_i32 s21, s20, 31
	s_lshl_b64 s[24:25], s[20:21], 20
	v_readlane_b32 s26, v236, 50
	v_readlane_b32 s27, v236, 51
	s_add_u32 s24, s26, s24
	s_addc_u32 s25, s27, s25
	s_and_b64 s[26:27], s[8:9], exec
	s_cselect_b32 s1, s25, s5
	s_cselect_b32 s3, s24, s4
	s_ashr_i32 s23, s22, 31
	s_lshl_b64 s[26:27], s[22:23], 20
	s_add_u32 s26, s10, s26
	s_addc_u32 s27, s11, s27
	s_and_b64 s[28:29], s[8:9], exec
	s_cselect_b32 s21, s27, s7
	s_cselect_b32 s23, s26, s6
	s_add_u32 s4, s4, 0x80080
	s_addc_u32 s5, s5, 0
	s_add_u32 s33, s6, 0x100
	s_addc_u32 s50, s7, 0
	s_mov_b32 s51, -2
	s_waitcnt vmcnt(0)
	ds_read_b128 v[128:131], v190
	ds_read_b128 v[132:135], v190 offset:1024
	ds_read_b128 v[136:139], v190 offset:2048
	ds_read_b128 v[140:143], v190 offset:3072
	ds_read_b128 v[144:147], v191
	ds_read_b128 v[148:151], v191 offset:1024
	ds_read_b128 v[152:155], v191 offset:2048
	ds_read_b128 v[156:159], v191 offset:3072
	s_add_u32 s6, s4, 0xfff80080
	s_addc_u32 s7, s5, -1
	s_cmp_eq_u32 s51, 28
	s_cselect_b32 s29, s1, s7
	s_cselect_b32 s28, s3, s6
	s_cselect_b32 s7, s21, s50
	s_cselect_b32 s6, s23, s33
	v_lshl_add_u64 v[184:185], s[4:5], 0, v[172:173]
	s_add_i32 m0, s31, 0xc000
	ds_read_b128 v[180:183], v192
	ds_read_b128 v[194:197], v192 offset:1024
	ds_read_b128 v[198:201], v192 offset:2048
	ds_read_b128 v[202:205], v192 offset:3072
	ds_read_b128 v[206:209], v192 offset:4096
	ds_read_b128 v[210:213], v192 offset:5120
	ds_read_b128 v[214:217], v192 offset:6144
	ds_read_b128 v[218:221], v192 offset:7168
	global_load_lds_dwordx4 v[184:185], off
	v_lshl_add_u64 v[184:185], s[4:5], 0, v[174:175]
	s_add_i32 m0, s31, 0xe000
	s_nop 0
	global_load_lds_dwordx4 v[184:185], off
	s_setprio 1
	s_waitcnt vmcnt(8)
	s_waitcnt lgkmcnt(0)
	s_barrier
	v_mfma_f32_16x16x32_bf16 v[124:127], v[128:131], v[180:183], 0
	v_mfma_f32_16x16x32_bf16 v[120:123], v[136:139], v[180:183], 0
	v_mfma_f32_16x16x32_bf16 v[108:111], v[128:131], v[198:201], 0
	v_mfma_f32_16x16x32_bf16 v[104:107], v[136:139], v[198:201], 0
	v_mfma_f32_16x16x32_bf16 v[92:95], v[128:131], v[206:209], 0
	v_mfma_f32_16x16x32_bf16 v[88:91], v[136:139], v[206:209], 0
	v_mfma_f32_16x16x32_bf16 v[76:79], v[128:131], v[214:217], 0
	v_mfma_f32_16x16x32_bf16 v[72:75], v[136:139], v[214:217], 0
	v_mfma_f32_16x16x32_bf16 v[124:127], v[132:135], v[194:197], v[124:127]
	v_mfma_f32_16x16x32_bf16 v[120:123], v[140:143], v[194:197], v[120:123]
	v_mfma_f32_16x16x32_bf16 v[108:111], v[132:135], v[202:205], v[108:111]
	v_mfma_f32_16x16x32_bf16 v[104:107], v[140:143], v[202:205], v[104:107]
	v_mfma_f32_16x16x32_bf16 v[92:95], v[132:135], v[210:213], v[92:95]
	v_mfma_f32_16x16x32_bf16 v[88:91], v[140:143], v[210:213], v[88:91]
	v_mfma_f32_16x16x32_bf16 v[76:79], v[132:135], v[218:221], v[76:79]
	v_mfma_f32_16x16x32_bf16 v[72:75], v[140:143], v[218:221], v[72:75]
	s_setprio 0
	s_setprio 1
	v_mfma_f32_16x16x32_bf16 v[116:119], v[144:147], v[180:183], 0
	v_mfma_f32_16x16x32_bf16 v[112:115], v[152:155], v[180:183], 0
	v_mfma_f32_16x16x32_bf16 v[100:103], v[144:147], v[198:201], 0
	v_mfma_f32_16x16x32_bf16 v[96:99], v[152:155], v[198:201], 0
	v_mfma_f32_16x16x32_bf16 v[84:87], v[144:147], v[206:209], 0
	v_mfma_f32_16x16x32_bf16 v[80:83], v[152:155], v[206:209], 0
	v_mfma_f32_16x16x32_bf16 v[68:71], v[144:147], v[214:217], 0
	v_mfma_f32_16x16x32_bf16 v[64:67], v[152:155], v[214:217], 0
	v_mfma_f32_16x16x32_bf16 v[116:119], v[148:151], v[194:197], v[116:119]
	v_mfma_f32_16x16x32_bf16 v[112:115], v[156:159], v[194:197], v[112:115]
	v_mfma_f32_16x16x32_bf16 v[100:103], v[148:151], v[202:205], v[100:103]
	v_mfma_f32_16x16x32_bf16 v[96:99], v[156:159], v[202:205], v[96:99]
	v_mfma_f32_16x16x32_bf16 v[84:87], v[148:151], v[210:213], v[84:87]
	v_mfma_f32_16x16x32_bf16 v[80:83], v[156:159], v[210:213], v[80:83]
	v_mfma_f32_16x16x32_bf16 v[68:71], v[148:151], v[218:221], v[68:71]
	v_mfma_f32_16x16x32_bf16 v[64:67], v[156:159], v[218:221], v[64:67]
	s_barrier
	s_setprio 0
	s_add_i32 s52, s43, s30
	v_lshl_add_u64 v[184:185], s[6:7], 0, v[164:165]
	s_mov_b32 m0, s52
	ds_read_b128 v[180:183], v192 offset:16384
	ds_read_b128 v[194:197], v192 offset:17408
	ds_read_b128 v[198:201], v192 offset:18432
	ds_read_b128 v[202:205], v192 offset:19456
	ds_read_b128 v[206:209], v192 offset:20480
	ds_read_b128 v[210:213], v192 offset:21504
	ds_read_b128 v[214:217], v192 offset:22528
	ds_read_b128 v[218:221], v192 offset:23552
	global_load_lds_dwordx4 v[184:185], off
	s_add_i32 m0, s52, 0x2000
	s_add_u32 s52, s6, 0x80000
	v_lshl_add_u64 v[222:223], s[6:7], 0, v[168:169]
	s_addc_u32 s53, s7, 0
	s_add_i32 s54, s44, s30
	global_load_lds_dwordx4 v[222:223], off
	v_lshl_add_u64 v[224:225], s[52:53], 0, v[164:165]
	s_mov_b32 m0, s54
	v_lshl_add_u64 v[226:227], s[28:29], 0, v[166:167]
	global_load_lds_dwordx4 v[224:225], off
	v_lshl_add_u64 v[224:225], s[52:53], 0, v[168:169]
	s_add_i32 m0, s54, 0x2000
	s_nop 0
	global_load_lds_dwordx4 v[224:225], off
	v_lshl_add_u64 v[224:225], s[28:29], 0, v[162:163]
	s_mov_b32 m0, s31
	s_nop 0
	global_load_lds_dwordx4 v[224:225], off
	s_mov_b32 m0, s34
	s_nop 0
	global_load_lds_dwordx4 v[226:227], off
	s_setprio 1
	s_waitcnt vmcnt(8)
	s_waitcnt lgkmcnt(0)
	s_barrier
; #define PG8_STAGE(bufoff, gbase, voff) do { _Pragma("unroll") for (int _i = 0; _i < 2; ++_i) \
;         __builtin_amdgcn_global_load_lds((const unsigned*)((const char*)(gbase) + (voff)[_i]), (PG8_LAS unsigned*)(lds + (bufoff) + ldsw + _i * 8192), 16, 0, 0); } while (0)
; #define PG8_LDA(dst, b, h) do { _Pragma("unroll") for (int m = 0; m < 4; ++m) _Pragma("unroll") for (int k = 0; k < 2; ++k) dst[m][k] = *(const PG8_LAS bf16x8*)(lds + PG8_SA(b, h) + aoff + m * 2048 + k * 1024); } while (0)
; #define PG8_LDB(dst, b, h) do { _Pragma("unroll") for (int n = 0; n < 2; ++n) _Pragma("unroll") for (int k = 0; k < 2; ++k) dst[n][k] = *(const PG8_LAS bf16x8*)(lds + PG8_SB(b, h) + boff + n * 2048 + k * 1024); } while (0)
; #define PG8_MMA(ai, bj, At, Bt) do { __builtin_amdgcn_s_setprio(1); _Pragma("unroll") for (int m = 0; m < 4; ++m) _Pragma("unroll") for (int n = 0; n < 2; ++n) _Pragma("unroll") for (int k = 0; k < 2; ++k) \
;         acc[ai][bj][m][n] = __builtin_amdgcn_mfma_f32_16x16x32_bf16(Bt[n][k], At[m][k], acc[ai][bj][m][n], 0, 0, 0); __builtin_amdgcn_s_setprio(0); } while (0)
; #define PG8_WAIT_V(n) asm volatile("s_waitcnt vmcnt(" #n ")" ::: "memory")
; #define PG8_WAIT_L(n) asm volatile("s_waitcnt lgkmcnt(" #n ")" ::: "memory")
; #define PG8_BAR __builtin_amdgcn_s_barrier()
; #define PG8_SCHED __builtin_amdgcn_sched_barrier(0)
; template <class Epi, class Sched, bool ALIGN_EPI = false, bool SP2 = false>
; __device__ __forceinline__ void gemm_phase(PG8_LAS unsigned char* lds, const Gemm g, const Sched& S, const Epi& E) {
;     ...
;             PG8_WAIT_V(8); PG8_WAIT_L(0); PG8_BAR; PG8_MMA(1, 0, At, B0); PG8_MMA(1, 1, At, B1); PG8_BAR; PG8_SCHED;
;             PG8_LDB(B0, 1, 0); PG8_LDB(B1, 1, 1); PG8_SCHED; PG8_LDA(At, 1, 0); PG8_STAGE(PG8_SA(0, 1), a2 + hstep, voffA);
;             PG8_WAIT_V(8); PG8_WAIT_L(0); PG8_BAR; PG8_MMA(0, 0, At, B0); PG8_MMA(0, 1, At, B1); PG8_BAR; PG8_SCHED;
;             PG8_LDA(At, 1, 1); PG8_STAGE(PG8_SB(1, 0), b3, voffB); PG8_STAGE(PG8_SB(1, 1), b3 + hstep, voffB); PG8_STAGE(PG8_SA(1, 0), a3, voffA);
	v_mfma_f32_16x16x32_bf16 v[60:63], v[128:131], v[180:183], 0
	v_mfma_f32_16x16x32_bf16 v[56:59], v[136:139], v[180:183], 0
	v_mfma_f32_16x16x32_bf16 v[44:47], v[128:131], v[198:201], 0
	v_mfma_f32_16x16x32_bf16 v[40:43], v[136:139], v[198:201], 0
	v_mfma_f32_16x16x32_bf16 v[28:31], v[128:131], v[206:209], 0
	v_mfma_f32_16x16x32_bf16 v[24:27], v[136:139], v[206:209], 0
	v_mfma_f32_16x16x32_bf16 v[12:15], v[128:131], v[214:217], 0
	v_mfma_f32_16x16x32_bf16 v[8:11], v[136:139], v[214:217], 0
	v_mfma_f32_16x16x32_bf16 v[60:63], v[132:135], v[194:197], v[60:63]
	v_mfma_f32_16x16x32_bf16 v[56:59], v[140:143], v[194:197], v[56:59]
	v_mfma_f32_16x16x32_bf16 v[44:47], v[132:135], v[202:205], v[44:47]
	v_mfma_f32_16x16x32_bf16 v[40:43], v[140:143], v[202:205], v[40:43]
	v_mfma_f32_16x16x32_bf16 v[28:31], v[132:135], v[210:213], v[28:31]
	v_mfma_f32_16x16x32_bf16 v[24:27], v[140:143], v[210:213], v[24:27]
	v_mfma_f32_16x16x32_bf16 v[12:15], v[132:135], v[218:221], v[12:15]
	v_mfma_f32_16x16x32_bf16 v[8:11], v[140:143], v[218:221], v[8:11]
	s_setprio 0
	s_setprio 1
	v_mfma_f32_16x16x32_bf16 v[52:55], v[144:147], v[180:183], 0
	v_mfma_f32_16x16x32_bf16 v[48:51], v[152:155], v[180:183], 0
	v_mfma_f32_16x16x32_bf16 v[36:39], v[144:147], v[198:201], 0
	v_mfma_f32_16x16x32_bf16 v[32:35], v[152:155], v[198:201], 0
	v_mfma_f32_16x16x32_bf16 v[20:23], v[144:147], v[206:209], 0
	v_mfma_f32_16x16x32_bf16 v[16:19], v[152:155], v[206:209], 0
	v_mfma_f32_16x16x32_bf16 v[4:7], v[144:147], v[214:217], 0
	v_mfma_f32_16x16x32_bf16 v[0:3], v[152:155], v[214:217], 0
	v_mfma_f32_16x16x32_bf16 v[52:55], v[148:151], v[194:197], v[52:55]
	v_mfma_f32_16x16x32_bf16 v[48:51], v[156:159], v[194:197], v[48:51]
	v_mfma_f32_16x16x32_bf16 v[36:39], v[148:151], v[202:205], v[36:39]
	v_mfma_f32_16x16x32_bf16 v[32:35], v[156:159], v[202:205], v[32:35]
	v_mfma_f32_16x16x32_bf16 v[20:23], v[148:151], v[210:213], v[20:23]
	v_mfma_f32_16x16x32_bf16 v[16:19], v[156:159], v[210:213], v[16:19]
	v_mfma_f32_16x16x32_bf16 v[4:7], v[148:151], v[218:221], v[4:7]
	v_mfma_f32_16x16x32_bf16 v[0:3], v[156:159], v[218:221], v[0:3]
	s_barrier
	s_setprio 0
	s_add_i32 s52, 0, 0x18000
	s_add_i32 s53, 0, 0x1c000
	v_add_u32_e32 v140, s52, v188
	v_add_u32_e32 v156, s53, v188
	ds_read_b128 v[128:131], v140
	ds_read_b128 v[132:135], v140 offset:1024
	ds_read_b128 v[136:139], v140 offset:2048
	ds_read_b128 v[140:143], v140 offset:3072
	ds_read_b128 v[144:147], v156
	ds_read_b128 v[148:151], v156 offset:1024
	ds_read_b128 v[152:155], v156 offset:2048
	ds_read_b128 v[156:159], v156 offset:3072
	s_add_u32 s28, s28, 0x80000
	s_addc_u32 s29, s29, 0
	s_mov_b32 m0, s35
	v_lshl_add_u64 v[228:229], s[28:29], 0, v[162:163]
	ds_read_b128 v[180:183], v192 offset:32768
	ds_read_b128 v[194:197], v192 offset:33792
	ds_read_b128 v[198:201], v192 offset:34816
	ds_read_b128 v[202:205], v192 offset:35840
	ds_read_b128 v[206:209], v192 offset:36864
	ds_read_b128 v[210:213], v192 offset:37888
	ds_read_b128 v[214:217], v192 offset:38912
	ds_read_b128 v[218:221], v192 offset:39936
	global_load_lds_dwordx4 v[228:229], off
	v_lshl_add_u64 v[228:229], s[28:29], 0, v[166:167]
	s_mov_b32 m0, s36
	s_nop 0
	global_load_lds_dwordx4 v[228:229], off
	s_setprio 1
	s_waitcnt vmcnt(8)
	s_waitcnt lgkmcnt(0)
	s_barrier
	v_mfma_f32_16x16x32_bf16 v[124:127], v[128:131], v[180:183], v[124:127]
	v_mfma_f32_16x16x32_bf16 v[120:123], v[136:139], v[180:183], v[120:123]
	v_mfma_f32_16x16x32_bf16 v[108:111], v[128:131], v[198:201], v[108:111]
	v_mfma_f32_16x16x32_bf16 v[104:107], v[136:139], v[198:201], v[104:107]
	v_mfma_f32_16x16x32_bf16 v[92:95], v[128:131], v[206:209], v[92:95]
	v_mfma_f32_16x16x32_bf16 v[88:91], v[136:139], v[206:209], v[88:91]
	v_mfma_f32_16x16x32_bf16 v[76:79], v[128:131], v[214:217], v[76:79]
	v_mfma_f32_16x16x32_bf16 v[72:75], v[136:139], v[214:217], v[72:75]
	v_mfma_f32_16x16x32_bf16 v[124:127], v[132:135], v[194:197], v[124:127]
	v_mfma_f32_16x16x32_bf16 v[120:123], v[140:143], v[194:197], v[120:123]
	v_mfma_f32_16x16x32_bf16 v[108:111], v[132:135], v[202:205], v[108:111]
	v_mfma_f32_16x16x32_bf16 v[104:107], v[140:143], v[202:205], v[104:107]
	v_mfma_f32_16x16x32_bf16 v[92:95], v[132:135], v[210:213], v[92:95]
	v_mfma_f32_16x16x32_bf16 v[88:91], v[140:143], v[210:213], v[88:91]
	v_mfma_f32_16x16x32_bf16 v[76:79], v[132:135], v[218:221], v[76:79]
	v_mfma_f32_16x16x32_bf16 v[72:75], v[140:143], v[218:221], v[72:75]
	s_setprio 0
	s_setprio 1
	v_mfma_f32_16x16x32_bf16 v[116:119], v[144:147], v[180:183], v[116:119]
	v_mfma_f32_16x16x32_bf16 v[112:115], v[152:155], v[180:183], v[112:115]
	v_mfma_f32_16x16x32_bf16 v[100:103], v[144:147], v[198:201], v[100:103]
	v_mfma_f32_16x16x32_bf16 v[96:99], v[152:155], v[198:201], v[96:99]
	v_mfma_f32_16x16x32_bf16 v[84:87], v[144:147], v[206:209], v[84:87]
	v_mfma_f32_16x16x32_bf16 v[80:83], v[152:155], v[206:209], v[80:83]
	v_mfma_f32_16x16x32_bf16 v[68:71], v[144:147], v[214:217], v[68:71]
	v_mfma_f32_16x16x32_bf16 v[64:67], v[152:155], v[214:217], v[64:67]
	v_mfma_f32_16x16x32_bf16 v[116:119], v[148:151], v[194:197], v[116:119]
	v_mfma_f32_16x16x32_bf16 v[112:115], v[156:159], v[194:197], v[112:115]
	v_mfma_f32_16x16x32_bf16 v[100:103], v[148:151], v[202:205], v[100:103]
	v_mfma_f32_16x16x32_bf16 v[96:99], v[156:159], v[202:205], v[96:99]
	v_mfma_f32_16x16x32_bf16 v[84:87], v[148:151], v[210:213], v[84:87]
	v_mfma_f32_16x16x32_bf16 v[80:83], v[156:159], v[210:213], v[80:83]
	v_mfma_f32_16x16x32_bf16 v[68:71], v[148:151], v[218:221], v[68:71]
	v_mfma_f32_16x16x32_bf16 v[64:67], v[156:159], v[218:221], v[64:67]
	s_barrier
; #define PG8_STAGE(bufoff, gbase, voff) do { _Pragma("unroll") for (int _i = 0; _i < 2; ++_i) \
;         __builtin_amdgcn_global_load_lds((const unsigned*)((const char*)(gbase) + (voff)[_i]), (PG8_LAS unsigned*)(lds + (bufoff) + ldsw + _i * 8192), 16, 0, 0); } while (0)
; #define PG8_LDA(dst, b, h) do { _Pragma("unroll") for (int m = 0; m < 4; ++m) _Pragma("unroll") for (int k = 0; k < 2; ++k) dst[m][k] = *(const PG8_LAS bf16x8*)(lds + PG8_SA(b, h) + aoff + m * 2048 + k * 1024); } while (0)
; #define PG8_MMA(ai, bj, At, Bt) do { __builtin_amdgcn_s_setprio(1); _Pragma("unroll") for (int m = 0; m < 4; ++m) _Pragma("unroll") for (int n = 0; n < 2; ++n) _Pragma("unroll") for (int k = 0; k < 2; ++k) \
;         acc[ai][bj][m][n] = __builtin_amdgcn_mfma_f32_16x16x32_bf16(Bt[n][k], At[m][k], acc[ai][bj][m][n], 0, 0, 0); __builtin_amdgcn_s_setprio(0); } while (0)
; #define PG8_WAIT_V(n) asm volatile("s_waitcnt vmcnt(" #n ")" ::: "memory")
; #define PG8_WAIT_L(n) asm volatile("s_waitcnt lgkmcnt(" #n ")" ::: "memory")
; #define PG8_BAR __builtin_amdgcn_s_barrier()
; #define PG8_SCHED __builtin_amdgcn_sched_barrier(0)
; template <class Epi, class Sched, bool ALIGN_EPI = false, bool SP2 = false>
; __device__ __forceinline__ void gemm_phase(PG8_LAS unsigned char* lds, const Gemm g, const Sched& S, const Epi& E) {
;     ...
;         for (int t = 0; t < nt; t += 2) {
;     ...
;             PG8_LDA(At, 1, 1); PG8_STAGE(PG8_SB(1, 0), b3, voffB); PG8_STAGE(PG8_SB(1, 1), b3 + hstep, voffB); PG8_STAGE(PG8_SA(1, 0), a3, voffA);
;             PG8_WAIT_V(8); PG8_WAIT_L(0); PG8_BAR; PG8_MMA(1, 0, At, B0); PG8_MMA(1, 1, At, B1); PG8_BAR; PG8_SCHED;
	s_setprio 0
	s_add_i32 s28, s52, s30
	v_lshl_add_u64 v[184:185], v[184:185], 0, s[16:17]
	s_mov_b32 m0, s28
	ds_read_b128 v[180:183], v192 offset:49152
	ds_read_b128 v[194:197], v192 offset:50176
	ds_read_b128 v[198:201], v192 offset:51200
	ds_read_b128 v[202:205], v192 offset:52224
	ds_read_b128 v[206:209], v192 offset:53248
	ds_read_b128 v[210:213], v192 offset:54272
	ds_read_b128 v[214:217], v192 offset:55296
	ds_read_b128 v[218:221], v192 offset:56320
	global_load_lds_dwordx4 v[184:185], off
	s_add_i32 m0, s28, 0x2000
	s_add_u32 s6, s6, 0x80080
	v_lshl_add_u64 v[184:185], v[222:223], 0, s[16:17]
	s_addc_u32 s7, s7, 0
	s_add_i32 s28, s53, s30
	global_load_lds_dwordx4 v[184:185], off
	v_lshl_add_u64 v[184:185], s[6:7], 0, v[164:165]
	s_mov_b32 m0, s28
	s_nop 0
	global_load_lds_dwordx4 v[184:185], off
	v_lshl_add_u64 v[184:185], s[6:7], 0, v[168:169]
	s_add_i32 m0, s28, 0x2000
	s_nop 0
	global_load_lds_dwordx4 v[184:185], off
	v_lshl_add_u64 v[184:185], v[224:225], 0, s[16:17]
	s_mov_b32 m0, s38
	s_nop 0
	global_load_lds_dwordx4 v[184:185], off
	v_lshl_add_u64 v[184:185], v[226:227], 0, s[16:17]
	s_mov_b32 m0, s39
	s_nop 0
	global_load_lds_dwordx4 v[184:185], off
	s_setprio 1
	s_waitcnt vmcnt(8)
	s_waitcnt lgkmcnt(0)
	s_barrier
	v_mfma_f32_16x16x32_bf16 v[60:63], v[128:131], v[180:183], v[60:63]
	v_mfma_f32_16x16x32_bf16 v[56:59], v[136:139], v[180:183], v[56:59]
	v_mfma_f32_16x16x32_bf16 v[44:47], v[128:131], v[198:201], v[44:47]
	v_mfma_f32_16x16x32_bf16 v[40:43], v[136:139], v[198:201], v[40:43]
	v_mfma_f32_16x16x32_bf16 v[28:31], v[128:131], v[206:209], v[28:31]
	v_mfma_f32_16x16x32_bf16 v[24:27], v[136:139], v[206:209], v[24:27]
	v_mfma_f32_16x16x32_bf16 v[12:15], v[128:131], v[214:217], v[12:15]
	v_mfma_f32_16x16x32_bf16 v[8:11], v[136:139], v[214:217], v[8:11]
	v_mfma_f32_16x16x32_bf16 v[60:63], v[132:135], v[194:197], v[60:63]
	v_mfma_f32_16x16x32_bf16 v[56:59], v[140:143], v[194:197], v[56:59]
	v_mfma_f32_16x16x32_bf16 v[44:47], v[132:135], v[202:205], v[44:47]
	v_mfma_f32_16x16x32_bf16 v[40:43], v[140:143], v[202:205], v[40:43]
	v_mfma_f32_16x16x32_bf16 v[28:31], v[132:135], v[210:213], v[28:31]
	v_mfma_f32_16x16x32_bf16 v[24:27], v[140:143], v[210:213], v[24:27]
	v_mfma_f32_16x16x32_bf16 v[12:15], v[132:135], v[218:221], v[12:15]
	v_mfma_f32_16x16x32_bf16 v[8:11], v[140:143], v[218:221], v[8:11]
	s_setprio 0
	s_setprio 1
	v_mfma_f32_16x16x32_bf16 v[52:55], v[144:147], v[180:183], v[52:55]
	v_mfma_f32_16x16x32_bf16 v[48:51], v[152:155], v[180:183], v[48:51]
	v_mfma_f32_16x16x32_bf16 v[36:39], v[144:147], v[198:201], v[36:39]
	v_mfma_f32_16x16x32_bf16 v[32:35], v[152:155], v[198:201], v[32:35]
	v_mfma_f32_16x16x32_bf16 v[20:23], v[144:147], v[206:209], v[20:23]
	v_mfma_f32_16x16x32_bf16 v[16:19], v[152:155], v[206:209], v[16:19]
	v_mfma_f32_16x16x32_bf16 v[4:7], v[144:147], v[214:217], v[4:7]
	v_mfma_f32_16x16x32_bf16 v[0:3], v[152:155], v[214:217], v[0:3]
	v_mfma_f32_16x16x32_bf16 v[52:55], v[148:151], v[194:197], v[52:55]
	v_mfma_f32_16x16x32_bf16 v[48:51], v[156:159], v[194:197], v[48:51]
	v_mfma_f32_16x16x32_bf16 v[36:39], v[148:151], v[202:205], v[36:39]
	v_mfma_f32_16x16x32_bf16 v[32:35], v[156:159], v[202:205], v[32:35]
	v_mfma_f32_16x16x32_bf16 v[20:23], v[148:151], v[210:213], v[20:23]
	v_mfma_f32_16x16x32_bf16 v[16:19], v[156:159], v[210:213], v[16:19]
	v_mfma_f32_16x16x32_bf16 v[4:7], v[148:151], v[218:221], v[4:7]
	v_mfma_f32_16x16x32_bf16 v[0:3], v[156:159], v[218:221], v[0:3]
	s_barrier
	s_setprio 0
	s_add_i32 s51, s51, 2
	s_add_u32 s4, s4, 0x100
	s_addc_u32 s5, s5, 0
	s_add_u32 s33, s33, 0x100
	s_addc_u32 s50, s50, 0
	s_cmp_gt_u32 s51, 29
	.p2align	6

;     __device__ __forceinline__ bool next(int i, Unit& u) const { if (!base.next(i >> 1, u)) return false; if (i & 1) { u.pm += 64; u.pn += 8; } return true; }
; #define PG8_STAGE(bufoff, gbase, voff) do { _Pragma("unroll") for (int _i = 0; _i < 2; ++_i) \
;         __builtin_amdgcn_global_load_lds((const unsigned*)((const char*)(gbase) + (voff)[_i]), (PG8_LAS unsigned*)(lds + (bufoff) + ldsw + _i * 8192), 16, 0, 0); } while (0)
; #define PG8_LDA(dst, b, h) do { _Pragma("unroll") for (int m = 0; m < 4; ++m) _Pragma("unroll") for (int k = 0; k < 2; ++k) dst[m][k] = *(const PG8_LAS bf16x8*)(lds + PG8_SA(b, h) + aoff + m * 2048 + k * 1024); } while (0)
; #define PG8_LDB(dst, b, h) do { _Pragma("unroll") for (int n = 0; n < 2; ++n) _Pragma("unroll") for (int k = 0; k < 2; ++k) dst[n][k] = *(const PG8_LAS bf16x8*)(lds + PG8_SB(b, h) + boff + n * 2048 + k * 1024); } while (0)
; #define PG8_WAIT_V(n) asm volatile("s_waitcnt vmcnt(" #n ")" ::: "memory")
; #define PG8_WAIT_L(n) asm volatile("s_waitcnt lgkmcnt(" #n ")" ::: "memory")
; #define PG8_BAR __builtin_amdgcn_s_barrier()
; #define PG8_SCHED __builtin_amdgcn_sched_barrier(0)
; template <class Epi, class Sched, bool ALIGN_EPI = false, bool SP2 = false>
; __device__ __forceinline__ void gemm_phase(PG8_LAS unsigned char* lds, const Gemm g, const Sched& S, const Epi& E) {
;     ...
;         const bool has_next = S.next(ui + 1, nxt);
;         const char* nA = has_next ? (const char*)g.A + (size_t)nxt.pm * tstep : cA; const char* nB = has_next ? (const char*)g.Bt + (size_t)nxt.pn * tstep : cB;
;         for (int t = 0; t < nt; t += 2) {
;             const bool last = (t == nt - 2);
;             const char* a1 = cA + (size_t)(t + 1) * kstep;
;             const char* a2 = last ? nA : cA + (size_t)(t + 2) * kstep; const char* b2 = last ? nB : cB + (size_t)(t + 2) * kstep;
;             const char* a3 = a2 + kstep; const char* b3 = b2 + kstep;
;             if (last && has_next) S.a_ready(nxt);
;             if constexpr (SP2) {
;             PG8_LDB(B0, 0, 0); PG8_LDB(B1, 0, 1); PG8_SCHED; PG8_LDA(At, 0, 0); PG8_STAGE(PG8_SA(1, 1), a1 + hstep, voffA);
;             PG8_WAIT_V(8); PG8_WAIT_L(0); PG8_BAR; PG8_MMA(0, 0, At, B0); PG8_MMA(0, 1, At, B1); PG8_BAR; PG8_SCHED;
;             PG8_LDA(At, 0, 1); PG8_STAGE(PG8_SB(0, 0), b2, voffB); PG8_STAGE(PG8_SB(0, 1), b2 + hstep, voffB); PG8_STAGE(PG8_SA(0, 0), a2, voffA);
.LBB0_571:
	s_bitcmp0_b32 s7, 0
	s_cselect_b64 s[16:17], -1, 0
	s_and_b64 s[16:17], s[16:17], s[4:5]
	s_add_i32 s7, s14, 64
	s_add_i32 s13, s12, 8
	s_and_b64 s[16:17], s[16:17], exec
	s_cselect_b32 s14, s7, s14
	s_cselect_b32 s12, s13, s12
	s_ashr_i32 s15, s14, 31
	s_lshl_b64 s[16:17], s[14:15], 19
	s_add_u32 s16, s29, s16
	s_addc_u32 s17, s30, s17
	s_and_b64 s[18:19], s[4:5], exec
	s_cselect_b32 s7, s17, s23
	s_cselect_b32 s15, s16, s22
	s_ashr_i32 s13, s12, 31
	s_lshl_b64 s[18:19], s[12:13], 19
	v_readlane_b32 s26, v236, 41
	v_readlane_b32 s27, v236, 42
	s_add_u32 s18, s26, s18
	s_addc_u32 s19, s27, s19
	s_and_b64 s[26:27], s[4:5], exec
	s_cselect_b32 s13, s19, s25
	s_cselect_b32 s21, s18, s24
	s_add_u32 s22, s22, 0x40080
	s_addc_u32 s23, s23, 0
	s_add_u32 s44, s24, 0x100
	s_addc_u32 s45, s25, 0
	s_mov_b32 s46, -2
	ds_read_b128 v[146:149], v159
	ds_read_b128 v[150:153], v159 offset:1024
	ds_read_b128 v[164:167], v159 offset:2048
	ds_read_b128 v[168:171], v159 offset:3072
	ds_read_b128 v[172:175], v161
	ds_read_b128 v[176:179], v161 offset:1024
	ds_read_b128 v[180:183], v161 offset:2048
	ds_read_b128 v[188:191], v161 offset:3072
	s_add_u32 s24, s22, 0xfffc0080
	s_addc_u32 s25, s23, -1
	s_cmp_eq_u32 s46, 12
	s_cselect_b32 s27, s7, s25
	s_cselect_b32 s26, s15, s24
	s_cselect_b32 s25, s13, s45
	s_cselect_b32 s24, s21, s44
	v_lshl_add_u64 v[154:155], s[22:23], 0, v[138:139]
	s_add_i32 m0, s31, 0xc000
	ds_read_b128 v[192:195], v162
	ds_read_b128 v[196:199], v162 offset:1024
	ds_read_b128 v[200:203], v162 offset:2048
	ds_read_b128 v[204:207], v162 offset:3072
	ds_read_b128 v[208:211], v162 offset:4096
	ds_read_b128 v[212:215], v162 offset:5120
	ds_read_b128 v[216:219], v162 offset:6144
	ds_read_b128 v[220:223], v162 offset:7168
	global_load_lds_dwordx4 v[154:155], off
	v_lshl_add_u64 v[154:155], s[22:23], 0, v[140:141]
	s_add_i32 m0, s31, 0xe000
	s_nop 0
	global_load_lds_dwordx4 v[154:155], off
	s_setprio 1
	s_waitcnt vmcnt(8)
	s_waitcnt lgkmcnt(0)
	s_barrier
	v_mfma_f32_16x16x32_bf16 v[124:127], v[146:149], v[192:195], 0
	v_mfma_f32_16x16x32_bf16 v[120:123], v[164:167], v[192:195], 0
	v_mfma_f32_16x16x32_bf16 v[108:111], v[146:149], v[200:203], 0
	v_mfma_f32_16x16x32_bf16 v[104:107], v[164:167], v[200:203], 0
	v_mfma_f32_16x16x32_bf16 v[92:95], v[146:149], v[208:211], 0
	v_mfma_f32_16x16x32_bf16 v[88:91], v[164:167], v[208:211], 0
	v_mfma_f32_16x16x32_bf16 v[76:79], v[146:149], v[216:219], 0
	v_mfma_f32_16x16x32_bf16 v[72:75], v[164:167], v[216:219], 0
	v_mfma_f32_16x16x32_bf16 v[124:127], v[150:153], v[196:199], v[124:127]
	v_mfma_f32_16x16x32_bf16 v[120:123], v[168:171], v[196:199], v[120:123]
	v_mfma_f32_16x16x32_bf16 v[108:111], v[150:153], v[204:207], v[108:111]
	v_mfma_f32_16x16x32_bf16 v[104:107], v[168:171], v[204:207], v[104:107]
	v_mfma_f32_16x16x32_bf16 v[92:95], v[150:153], v[212:215], v[92:95]
	v_mfma_f32_16x16x32_bf16 v[88:91], v[168:171], v[212:215], v[88:91]
	v_mfma_f32_16x16x32_bf16 v[76:79], v[150:153], v[220:223], v[76:79]
	v_mfma_f32_16x16x32_bf16 v[72:75], v[168:171], v[220:223], v[72:75]
	s_setprio 0
	s_setprio 1
	v_mfma_f32_16x16x32_bf16 v[116:119], v[172:175], v[192:195], 0
	v_mfma_f32_16x16x32_bf16 v[112:115], v[180:183], v[192:195], 0
	v_mfma_f32_16x16x32_bf16 v[100:103], v[172:175], v[200:203], 0
	v_mfma_f32_16x16x32_bf16 v[96:99], v[180:183], v[200:203], 0
	v_mfma_f32_16x16x32_bf16 v[84:87], v[172:175], v[208:211], 0
	v_mfma_f32_16x16x32_bf16 v[80:83], v[180:183], v[208:211], 0
	v_mfma_f32_16x16x32_bf16 v[68:71], v[172:175], v[216:219], 0
	v_mfma_f32_16x16x32_bf16 v[64:67], v[180:183], v[216:219], 0
	v_mfma_f32_16x16x32_bf16 v[116:119], v[176:179], v[196:199], v[116:119]
	v_mfma_f32_16x16x32_bf16 v[112:115], v[188:191], v[196:199], v[112:115]
	v_mfma_f32_16x16x32_bf16 v[100:103], v[176:179], v[204:207], v[100:103]
	v_mfma_f32_16x16x32_bf16 v[96:99], v[188:191], v[204:207], v[96:99]
	v_mfma_f32_16x16x32_bf16 v[84:87], v[176:179], v[212:215], v[84:87]
	v_mfma_f32_16x16x32_bf16 v[80:83], v[188:191], v[212:215], v[80:83]
	v_mfma_f32_16x16x32_bf16 v[68:71], v[176:179], v[220:223], v[68:71]
	v_mfma_f32_16x16x32_bf16 v[64:67], v[188:191], v[220:223], v[64:67]
	s_barrier
	s_setprio 0
	s_add_i32 s47, s39, s28
	v_lshl_add_u64 v[154:155], s[24:25], 0, v[130:131]
	s_mov_b32 m0, s47
	ds_read_b128 v[192:195], v162 offset:16384
	ds_read_b128 v[196:199], v162 offset:17408
	ds_read_b128 v[200:203], v162 offset:18432
	ds_read_b128 v[204:207], v162 offset:19456
	ds_read_b128 v[208:211], v162 offset:20480
	ds_read_b128 v[212:215], v162 offset:21504
	ds_read_b128 v[216:219], v162 offset:22528
	ds_read_b128 v[220:223], v162 offset:23552
	global_load_lds_dwordx4 v[154:155], off
	s_add_i32 m0, s47, 0x2000
	s_add_u32 s48, s24, 0x40000
	v_lshl_add_u64 v[184:185], s[24:25], 0, v[134:135]
	s_addc_u32 s49, s25, 0
	s_add_i32 s47, s40, s28
	global_load_lds_dwordx4 v[184:185], off
	v_lshl_add_u64 v[224:225], s[48:49], 0, v[130:131]
	s_mov_b32 m0, s47
	v_lshl_add_u64 v[226:227], s[26:27], 0, v[132:133]
	global_load_lds_dwordx4 v[224:225], off
	v_lshl_add_u64 v[224:225], s[48:49], 0, v[134:135]
	s_add_i32 m0, s47, 0x2000
	s_nop 0
	global_load_lds_dwordx4 v[224:225], off
	v_lshl_add_u64 v[224:225], s[26:27], 0, v[128:129]
	s_mov_b32 m0, s31
	s_nop 0
	global_load_lds_dwordx4 v[224:225], off
	s_mov_b32 m0, s33
	s_nop 0
	global_load_lds_dwordx4 v[226:227], off
	s_setprio 1
	s_waitcnt vmcnt(8)
	s_waitcnt lgkmcnt(0)
	s_barrier
; #define PG8_STAGE(bufoff, gbase, voff) do { _Pragma("unroll") for (int _i = 0; _i < 2; ++_i) \
;         __builtin_amdgcn_global_load_lds((const unsigned*)((const char*)(gbase) + (voff)[_i]), (PG8_LAS unsigned*)(lds + (bufoff) + ldsw + _i * 8192), 16, 0, 0); } while (0)
; #define PG8_LDA(dst, b, h) do { _Pragma("unroll") for (int m = 0; m < 4; ++m) _Pragma("unroll") for (int k = 0; k < 2; ++k) dst[m][k] = *(const PG8_LAS bf16x8*)(lds + PG8_SA(b, h) + aoff + m * 2048 + k * 1024); } while (0)
; #define PG8_LDB(dst, b, h) do { _Pragma("unroll") for (int n = 0; n < 2; ++n) _Pragma("unroll") for (int k = 0; k < 2; ++k) dst[n][k] = *(const PG8_LAS bf16x8*)(lds + PG8_SB(b, h) + boff + n * 2048 + k * 1024); } while (0)
; #define PG8_MMA(ai, bj, At, Bt) do { __builtin_amdgcn_s_setprio(1); _Pragma("unroll") for (int m = 0; m < 4; ++m) _Pragma("unroll") for (int n = 0; n < 2; ++n) _Pragma("unroll") for (int k = 0; k < 2; ++k) \
;         acc[ai][bj][m][n] = __builtin_amdgcn_mfma_f32_16x16x32_bf16(Bt[n][k], At[m][k], acc[ai][bj][m][n], 0, 0, 0); __builtin_amdgcn_s_setprio(0); } while (0)
; #define PG8_WAIT_V(n) asm volatile("s_waitcnt vmcnt(" #n ")" ::: "memory")
; #define PG8_WAIT_L(n) asm volatile("s_waitcnt lgkmcnt(" #n ")" ::: "memory")
; #define PG8_BAR __builtin_amdgcn_s_barrier()
; #define PG8_SCHED __builtin_amdgcn_sched_barrier(0)
; template <class Epi, class Sched, bool ALIGN_EPI = false, bool SP2 = false>
; __device__ __forceinline__ void gemm_phase(PG8_LAS unsigned char* lds, const Gemm g, const Sched& S, const Epi& E) {
;     ...
;             PG8_WAIT_V(8); PG8_WAIT_L(0); PG8_BAR; PG8_MMA(1, 0, At, B0); PG8_MMA(1, 1, At, B1); PG8_BAR; PG8_SCHED;
;             PG8_LDB(B0, 1, 0); PG8_LDB(B1, 1, 1); PG8_SCHED; PG8_LDA(At, 1, 0); PG8_STAGE(PG8_SA(0, 1), a2 + hstep, voffA);
;             PG8_WAIT_V(8); PG8_WAIT_L(0); PG8_BAR; PG8_MMA(0, 0, At, B0); PG8_MMA(0, 1, At, B1); PG8_BAR; PG8_SCHED;
;             PG8_LDA(At, 1, 1); PG8_STAGE(PG8_SB(1, 0), b3, voffB); PG8_STAGE(PG8_SB(1, 1), b3 + hstep, voffB); PG8_STAGE(PG8_SA(1, 0), a3, voffA);
	v_mfma_f32_16x16x32_bf16 v[60:63], v[146:149], v[192:195], 0
	v_mfma_f32_16x16x32_bf16 v[56:59], v[164:167], v[192:195], 0
	v_mfma_f32_16x16x32_bf16 v[44:47], v[146:149], v[200:203], 0
	v_mfma_f32_16x16x32_bf16 v[40:43], v[164:167], v[200:203], 0
	v_mfma_f32_16x16x32_bf16 v[28:31], v[146:149], v[208:211], 0
	v_mfma_f32_16x16x32_bf16 v[24:27], v[164:167], v[208:211], 0
	v_mfma_f32_16x16x32_bf16 v[12:15], v[146:149], v[216:219], 0
	v_mfma_f32_16x16x32_bf16 v[8:11], v[164:167], v[216:219], 0
	v_mfma_f32_16x16x32_bf16 v[60:63], v[150:153], v[196:199], v[60:63]
	v_mfma_f32_16x16x32_bf16 v[56:59], v[168:171], v[196:199], v[56:59]
	v_mfma_f32_16x16x32_bf16 v[44:47], v[150:153], v[204:207], v[44:47]
	v_mfma_f32_16x16x32_bf16 v[40:43], v[168:171], v[204:207], v[40:43]
	v_mfma_f32_16x16x32_bf16 v[28:31], v[150:153], v[212:215], v[28:31]
	v_mfma_f32_16x16x32_bf16 v[24:27], v[168:171], v[212:215], v[24:27]
	v_mfma_f32_16x16x32_bf16 v[12:15], v[150:153], v[220:223], v[12:15]
	v_mfma_f32_16x16x32_bf16 v[8:11], v[168:171], v[220:223], v[8:11]
	s_setprio 0
	s_setprio 1
	v_mfma_f32_16x16x32_bf16 v[52:55], v[172:175], v[192:195], 0
	v_mfma_f32_16x16x32_bf16 v[48:51], v[180:183], v[192:195], 0
	v_mfma_f32_16x16x32_bf16 v[36:39], v[172:175], v[200:203], 0
	v_mfma_f32_16x16x32_bf16 v[32:35], v[180:183], v[200:203], 0
	v_mfma_f32_16x16x32_bf16 v[20:23], v[172:175], v[208:211], 0
	v_mfma_f32_16x16x32_bf16 v[16:19], v[180:183], v[208:211], 0
	v_mfma_f32_16x16x32_bf16 v[4:7], v[172:175], v[216:219], 0
	v_mfma_f32_16x16x32_bf16 v[0:3], v[180:183], v[216:219], 0
	v_mfma_f32_16x16x32_bf16 v[52:55], v[176:179], v[196:199], v[52:55]
	v_mfma_f32_16x16x32_bf16 v[48:51], v[188:191], v[196:199], v[48:51]
	v_mfma_f32_16x16x32_bf16 v[36:39], v[176:179], v[204:207], v[36:39]
	v_mfma_f32_16x16x32_bf16 v[32:35], v[188:191], v[204:207], v[32:35]
	v_mfma_f32_16x16x32_bf16 v[20:23], v[176:179], v[212:215], v[20:23]
	v_mfma_f32_16x16x32_bf16 v[16:19], v[188:191], v[212:215], v[16:19]
	v_mfma_f32_16x16x32_bf16 v[4:7], v[176:179], v[220:223], v[4:7]
	v_mfma_f32_16x16x32_bf16 v[0:3], v[188:191], v[220:223], v[0:3]
	s_barrier
	s_setprio 0
	s_add_i32 s47, 0, 0x18000
	v_add_u32_e32 v136, s47, v157
	s_add_i32 s48, 0, 0x1c000
	ds_read_b128 v[146:149], v136
	ds_read_b128 v[150:153], v136 offset:1024
	ds_read_b128 v[164:167], v136 offset:2048
	ds_read_b128 v[168:171], v136 offset:3072
	v_add_u32_e32 v136, s48, v157
	ds_read_b128 v[172:175], v136
	ds_read_b128 v[176:179], v136 offset:1024
	ds_read_b128 v[180:183], v136 offset:2048
	ds_read_b128 v[188:191], v136 offset:3072
	s_add_u32 s26, s26, 0x40000
	s_addc_u32 s27, s27, 0
	s_mov_b32 m0, s34
	v_lshl_add_u64 v[228:229], s[26:27], 0, v[128:129]
	ds_read_b128 v[192:195], v162 offset:32768
	ds_read_b128 v[196:199], v162 offset:33792
	ds_read_b128 v[200:203], v162 offset:34816
	ds_read_b128 v[204:207], v162 offset:35840
	ds_read_b128 v[208:211], v162 offset:36864
	ds_read_b128 v[212:215], v162 offset:37888
	ds_read_b128 v[216:219], v162 offset:38912
	ds_read_b128 v[220:223], v162 offset:39936
	global_load_lds_dwordx4 v[228:229], off
	v_lshl_add_u64 v[228:229], s[26:27], 0, v[132:133]
	s_mov_b32 m0, s35
	s_nop 0
	global_load_lds_dwordx4 v[228:229], off
	s_setprio 1
	s_waitcnt vmcnt(8)
	s_waitcnt lgkmcnt(0)
	s_barrier
	v_mfma_f32_16x16x32_bf16 v[124:127], v[146:149], v[192:195], v[124:127]
	v_mfma_f32_16x16x32_bf16 v[120:123], v[164:167], v[192:195], v[120:123]
	v_mfma_f32_16x16x32_bf16 v[108:111], v[146:149], v[200:203], v[108:111]
	v_mfma_f32_16x16x32_bf16 v[104:107], v[164:167], v[200:203], v[104:107]
	v_mfma_f32_16x16x32_bf16 v[92:95], v[146:149], v[208:211], v[92:95]
	v_mfma_f32_16x16x32_bf16 v[88:91], v[164:167], v[208:211], v[88:91]
	v_mfma_f32_16x16x32_bf16 v[76:79], v[146:149], v[216:219], v[76:79]
	v_mfma_f32_16x16x32_bf16 v[72:75], v[164:167], v[216:219], v[72:75]
	v_mfma_f32_16x16x32_bf16 v[124:127], v[150:153], v[196:199], v[124:127]
	v_mfma_f32_16x16x32_bf16 v[120:123], v[168:171], v[196:199], v[120:123]
	v_mfma_f32_16x16x32_bf16 v[108:111], v[150:153], v[204:207], v[108:111]
	v_mfma_f32_16x16x32_bf16 v[104:107], v[168:171], v[204:207], v[104:107]
	v_mfma_f32_16x16x32_bf16 v[92:95], v[150:153], v[212:215], v[92:95]
	v_mfma_f32_16x16x32_bf16 v[88:91], v[168:171], v[212:215], v[88:91]
	v_mfma_f32_16x16x32_bf16 v[76:79], v[150:153], v[220:223], v[76:79]
	v_mfma_f32_16x16x32_bf16 v[72:75], v[168:171], v[220:223], v[72:75]
	s_setprio 0
	s_setprio 1
	v_mfma_f32_16x16x32_bf16 v[116:119], v[172:175], v[192:195], v[116:119]
	v_mfma_f32_16x16x32_bf16 v[112:115], v[180:183], v[192:195], v[112:115]
	v_mfma_f32_16x16x32_bf16 v[100:103], v[172:175], v[200:203], v[100:103]
	v_mfma_f32_16x16x32_bf16 v[96:99], v[180:183], v[200:203], v[96:99]
	v_mfma_f32_16x16x32_bf16 v[84:87], v[172:175], v[208:211], v[84:87]
	v_mfma_f32_16x16x32_bf16 v[80:83], v[180:183], v[208:211], v[80:83]
	v_mfma_f32_16x16x32_bf16 v[68:71], v[172:175], v[216:219], v[68:71]
	v_mfma_f32_16x16x32_bf16 v[64:67], v[180:183], v[216:219], v[64:67]
	v_mfma_f32_16x16x32_bf16 v[116:119], v[176:179], v[196:199], v[116:119]
	v_mfma_f32_16x16x32_bf16 v[112:115], v[188:191], v[196:199], v[112:115]
	v_mfma_f32_16x16x32_bf16 v[100:103], v[176:179], v[204:207], v[100:103]
	v_mfma_f32_16x16x32_bf16 v[96:99], v[188:191], v[204:207], v[96:99]
	v_mfma_f32_16x16x32_bf16 v[84:87], v[176:179], v[212:215], v[84:87]
	v_mfma_f32_16x16x32_bf16 v[80:83], v[188:191], v[212:215], v[80:83]
	v_mfma_f32_16x16x32_bf16 v[68:71], v[176:179], v[220:223], v[68:71]
	v_mfma_f32_16x16x32_bf16 v[64:67], v[188:191], v[220:223], v[64:67]
	s_barrier
; #define PG8_STAGE(bufoff, gbase, voff) do { _Pragma("unroll") for (int _i = 0; _i < 2; ++_i) \
;         __builtin_amdgcn_global_load_lds((const unsigned*)((const char*)(gbase) + (voff)[_i]), (PG8_LAS unsigned*)(lds + (bufoff) + ldsw + _i * 8192), 16, 0, 0); } while (0)
; #define PG8_LDA(dst, b, h) do { _Pragma("unroll") for (int m = 0; m < 4; ++m) _Pragma("unroll") for (int k = 0; k < 2; ++k) dst[m][k] = *(const PG8_LAS bf16x8*)(lds + PG8_SA(b, h) + aoff + m * 2048 + k * 1024); } while (0)
; #define PG8_MMA(ai, bj, At, Bt) do { __builtin_amdgcn_s_setprio(1); _Pragma("unroll") for (int m = 0; m < 4; ++m) _Pragma("unroll") for (int n = 0; n < 2; ++n) _Pragma("unroll") for (int k = 0; k < 2; ++k) \
;         acc[ai][bj][m][n] = __builtin_amdgcn_mfma_f32_16x16x32_bf16(Bt[n][k], At[m][k], acc[ai][bj][m][n], 0, 0, 0); __builtin_amdgcn_s_setprio(0); } while (0)
; #define PG8_WAIT_V(n) asm volatile("s_waitcnt vmcnt(" #n ")" ::: "memory")
; #define PG8_WAIT_L(n) asm volatile("s_waitcnt lgkmcnt(" #n ")" ::: "memory")
; #define PG8_BAR __builtin_amdgcn_s_barrier()
; #define PG8_SCHED __builtin_amdgcn_sched_barrier(0)
; template <class Epi, class Sched, bool ALIGN_EPI = false, bool SP2 = false>
; __device__ __forceinline__ void gemm_phase(PG8_LAS unsigned char* lds, const Gemm g, const Sched& S, const Epi& E) {
;     ...
;         for (int t = 0; t < nt; t += 2) {
;     ...
;             PG8_LDA(At, 1, 1); PG8_STAGE(PG8_SB(1, 0), b3, voffB); PG8_STAGE(PG8_SB(1, 1), b3 + hstep, voffB); PG8_STAGE(PG8_SA(1, 0), a3, voffA);
;             PG8_WAIT_V(8); PG8_WAIT_L(0); PG8_BAR; PG8_MMA(1, 0, At, B0); PG8_MMA(1, 1, At, B1); PG8_BAR; PG8_SCHED;
	s_setprio 0
	s_add_i32 s26, s47, s28
	v_lshl_add_u64 v[154:155], v[154:155], 0, s[8:9]
	s_mov_b32 m0, s26
	ds_read_b128 v[192:195], v162 offset:49152
	ds_read_b128 v[196:199], v162 offset:50176
	ds_read_b128 v[200:203], v162 offset:51200
	ds_read_b128 v[204:207], v162 offset:52224
	ds_read_b128 v[208:211], v162 offset:53248
	ds_read_b128 v[212:215], v162 offset:54272
	ds_read_b128 v[216:219], v162 offset:55296
	ds_read_b128 v[220:223], v162 offset:56320
	global_load_lds_dwordx4 v[154:155], off
	s_add_i32 m0, s26, 0x2000
	s_add_u32 s24, s24, 0x40080
	v_lshl_add_u64 v[154:155], v[184:185], 0, s[8:9]
	s_addc_u32 s25, s25, 0
	s_add_i32 s26, s48, s28
	global_load_lds_dwordx4 v[154:155], off
	v_lshl_add_u64 v[154:155], s[24:25], 0, v[130:131]
	s_mov_b32 m0, s26
	s_nop 0
	global_load_lds_dwordx4 v[154:155], off
	v_lshl_add_u64 v[154:155], s[24:25], 0, v[134:135]
	s_add_i32 m0, s26, 0x2000
	s_nop 0
	global_load_lds_dwordx4 v[154:155], off
	v_lshl_add_u64 v[154:155], v[224:225], 0, s[8:9]
	s_mov_b32 m0, s36
	s_nop 0
	global_load_lds_dwordx4 v[154:155], off
	v_lshl_add_u64 v[154:155], v[226:227], 0, s[8:9]
	s_mov_b32 m0, s37
	s_nop 0
	global_load_lds_dwordx4 v[154:155], off
	s_setprio 1
	s_waitcnt vmcnt(8)
	s_waitcnt lgkmcnt(0)
	s_barrier
	v_mfma_f32_16x16x32_bf16 v[60:63], v[146:149], v[192:195], v[60:63]
	v_mfma_f32_16x16x32_bf16 v[56:59], v[164:167], v[192:195], v[56:59]
	v_mfma_f32_16x16x32_bf16 v[44:47], v[146:149], v[200:203], v[44:47]
	v_mfma_f32_16x16x32_bf16 v[40:43], v[164:167], v[200:203], v[40:43]
	v_mfma_f32_16x16x32_bf16 v[28:31], v[146:149], v[208:211], v[28:31]
	v_mfma_f32_16x16x32_bf16 v[24:27], v[164:167], v[208:211], v[24:27]
	v_mfma_f32_16x16x32_bf16 v[12:15], v[146:149], v[216:219], v[12:15]
	v_mfma_f32_16x16x32_bf16 v[8:11], v[164:167], v[216:219], v[8:11]
	v_mfma_f32_16x16x32_bf16 v[60:63], v[150:153], v[196:199], v[60:63]
	v_mfma_f32_16x16x32_bf16 v[56:59], v[168:171], v[196:199], v[56:59]
	v_mfma_f32_16x16x32_bf16 v[44:47], v[150:153], v[204:207], v[44:47]
	v_mfma_f32_16x16x32_bf16 v[40:43], v[168:171], v[204:207], v[40:43]
	v_mfma_f32_16x16x32_bf16 v[28:31], v[150:153], v[212:215], v[28:31]
	v_mfma_f32_16x16x32_bf16 v[24:27], v[168:171], v[212:215], v[24:27]
	v_mfma_f32_16x16x32_bf16 v[12:15], v[150:153], v[220:223], v[12:15]
	v_mfma_f32_16x16x32_bf16 v[8:11], v[168:171], v[220:223], v[8:11]
	s_setprio 0
	s_setprio 1
	v_mfma_f32_16x16x32_bf16 v[52:55], v[172:175], v[192:195], v[52:55]
	v_mfma_f32_16x16x32_bf16 v[48:51], v[180:183], v[192:195], v[48:51]
	v_mfma_f32_16x16x32_bf16 v[36:39], v[172:175], v[200:203], v[36:39]
	v_mfma_f32_16x16x32_bf16 v[32:35], v[180:183], v[200:203], v[32:35]
	v_mfma_f32_16x16x32_bf16 v[20:23], v[172:175], v[208:211], v[20:23]
	v_mfma_f32_16x16x32_bf16 v[16:19], v[180:183], v[208:211], v[16:19]
	v_mfma_f32_16x16x32_bf16 v[4:7], v[172:175], v[216:219], v[4:7]
	v_mfma_f32_16x16x32_bf16 v[0:3], v[180:183], v[216:219], v[0:3]
	v_mfma_f32_16x16x32_bf16 v[52:55], v[176:179], v[196:199], v[52:55]
	v_mfma_f32_16x16x32_bf16 v[48:51], v[188:191], v[196:199], v[48:51]
	v_mfma_f32_16x16x32_bf16 v[36:39], v[176:179], v[204:207], v[36:39]
	v_mfma_f32_16x16x32_bf16 v[32:35], v[188:191], v[204:207], v[32:35]
	v_mfma_f32_16x16x32_bf16 v[20:23], v[176:179], v[212:215], v[20:23]
	v_mfma_f32_16x16x32_bf16 v[16:19], v[188:191], v[212:215], v[16:19]
	v_mfma_f32_16x16x32_bf16 v[4:7], v[176:179], v[220:223], v[4:7]
	v_mfma_f32_16x16x32_bf16 v[0:3], v[188:191], v[220:223], v[0:3]
	s_barrier
	s_setprio 0
	s_add_i32 s46, s46, 2
	s_add_u32 s22, s22, 0x100
	s_addc_u32 s23, s23, 0
	s_add_u32 s44, s44, 0x100
	s_addc_u32 s45, s45, 0
	s_cmp_gt_u32 s46, 13
	.p2align	6

;     __device__ __forceinline__ bool next(int i, Unit& u) const { if (!base.next(i >> 1, u)) return false; if (i & 1) { u.pm += 64; u.pn += 8; } return true; }
; #define PG8_STAGE(bufoff, gbase, voff) do { _Pragma("unroll") for (int _i = 0; _i < 2; ++_i) \
;         __builtin_amdgcn_global_load_lds((const unsigned*)((const char*)(gbase) + (voff)[_i]), (PG8_LAS unsigned*)(lds + (bufoff) + ldsw + _i * 8192), 16, 0, 0); } while (0)
; #define PG8_LDA(dst, b, h) do { _Pragma("unroll") for (int m = 0; m < 4; ++m) _Pragma("unroll") for (int k = 0; k < 2; ++k) dst[m][k] = *(const PG8_LAS bf16x8*)(lds + PG8_SA(b, h) + aoff + m * 2048 + k * 1024); } while (0)
; #define PG8_LDB(dst, b, h) do { _Pragma("unroll") for (int n = 0; n < 2; ++n) _Pragma("unroll") for (int k = 0; k < 2; ++k) dst[n][k] = *(const PG8_LAS bf16x8*)(lds + PG8_SB(b, h) + boff + n * 2048 + k * 1024); } while (0)
; #define PG8_WAIT_V(n) asm volatile("s_waitcnt vmcnt(" #n ")" ::: "memory")
; #define PG8_WAIT_L(n) asm volatile("s_waitcnt lgkmcnt(" #n ")" ::: "memory")
; #define PG8_BAR __builtin_amdgcn_s_barrier()
; #define PG8_SCHED __builtin_amdgcn_sched_barrier(0)
; template <class Epi, class Sched, bool ALIGN_EPI = false, bool SP2 = false>
; __device__ __forceinline__ void gemm_phase(PG8_LAS unsigned char* lds, const Gemm g, const Sched& S, const Epi& E) {
;     ...
;         const bool has_next = S.next(ui + 1, nxt);
;         const char* nA = has_next ? (const char*)g.A + (size_t)nxt.pm * tstep : cA; const char* nB = has_next ? (const char*)g.Bt + (size_t)nxt.pn * tstep : cB;
;         for (int t = 0; t < nt; t += 2) {
;             const bool last = (t == nt - 2);
;             const char* a1 = cA + (size_t)(t + 1) * kstep;
;             const char* a2 = last ? nA : cA + (size_t)(t + 2) * kstep; const char* b2 = last ? nB : cB + (size_t)(t + 2) * kstep;
;             const char* a3 = a2 + kstep; const char* b3 = b2 + kstep;
;             if (last && has_next) S.a_ready(nxt);
;             if constexpr (SP2) {
;             PG8_LDB(B0, 0, 0); PG8_LDB(B1, 0, 1); PG8_SCHED; PG8_LDA(At, 0, 0); PG8_STAGE(PG8_SA(1, 1), a1 + hstep, voffA);
;             PG8_WAIT_V(8); PG8_WAIT_L(0); PG8_BAR; PG8_MMA(0, 0, At, B0); PG8_MMA(0, 1, At, B1); PG8_BAR; PG8_SCHED;
;             PG8_LDA(At, 0, 1); PG8_STAGE(PG8_SB(0, 0), b2, voffB); PG8_STAGE(PG8_SB(0, 1), b2 + hstep, voffB); PG8_STAGE(PG8_SA(0, 0), a2, voffA);
.LBB0_893:
	s_ashr_i32 s25, s24, 31
	s_lshl_b64 s[28:29], s[24:25], 20
	v_readlane_b32 s30, v236, 50
	v_readlane_b32 s31, v236, 51
	s_add_u32 s28, s30, s28
	s_addc_u32 s29, s31, s29
	s_and_b64 s[30:31], s[6:7], exec
	s_cselect_b32 s25, s29, s39
	s_cselect_b32 s35, s28, s38
	s_ashr_i32 s27, s26, 31
	s_lshl_b64 s[30:31], s[26:27], 20
	v_readlane_b32 s42, v236, 43
	v_readlane_b32 s43, v236, 44
	s_add_u32 s30, s42, s30
	s_addc_u32 s31, s43, s31
	s_and_b64 s[42:43], s[6:7], exec
	s_cselect_b32 s27, s31, s41
	s_cselect_b32 s55, s30, s40
	s_add_u32 s38, s38, 0x80080
	s_addc_u32 s39, s39, 0
	s_add_u32 s56, s40, 0x100
	s_addc_u32 s57, s41, 0
	s_mov_b32 s58, -2
	s_waitcnt lgkmcnt(0)
	ds_read_b128 v[72:75], v169
	ds_read_b128 v[84:87], v169 offset:1024
	ds_read_b128 v[92:95], v169 offset:2048
	ds_read_b128 v[96:99], v169 offset:3072
	ds_read_b128 v[156:159], v170
	ds_read_b128 v[160:163], v170 offset:1024
	ds_read_b128 v[174:177], v170 offset:2048
	ds_read_b128 v[178:181], v170 offset:3072
	s_add_u32 s40, s38, 0xfff80080
	s_addc_u32 s41, s39, -1
	s_cmp_eq_u32 s58, 28
	s_cselect_b32 s43, s25, s41
	s_cselect_b32 s42, s35, s40
	s_cselect_b32 s41, s27, s57
	s_cselect_b32 s40, s55, s56
	v_lshl_add_u64 v[164:165], s[38:39], 0, v[148:149]
	s_add_i32 m0, s37, 0xc000
	ds_read_b128 v[182:185], v171
	ds_read_b128 v[188:191], v171 offset:1024
	ds_read_b128 v[192:195], v171 offset:2048
	ds_read_b128 v[196:199], v171 offset:3072
	ds_read_b128 v[200:203], v171 offset:4096
	ds_read_b128 v[204:207], v171 offset:5120
	ds_read_b128 v[208:211], v171 offset:6144
	ds_read_b128 v[212:215], v171 offset:7168
	global_load_lds_dwordx4 v[164:165], off
	v_lshl_add_u64 v[164:165], s[38:39], 0, v[150:151]
	s_add_i32 m0, s37, 0xe000
	s_nop 0
	global_load_lds_dwordx4 v[164:165], off
	s_setprio 1
	s_waitcnt vmcnt(8)
	s_waitcnt lgkmcnt(0)
	s_barrier
	v_mfma_f32_16x16x32_bf16 v[140:143], v[72:75], v[182:185], 0
	v_mfma_f32_16x16x32_bf16 v[136:139], v[92:95], v[182:185], 0
	v_mfma_f32_16x16x32_bf16 v[124:127], v[72:75], v[192:195], 0
	v_mfma_f32_16x16x32_bf16 v[120:123], v[92:95], v[192:195], 0
	v_mfma_f32_16x16x32_bf16 v[108:111], v[72:75], v[200:203], 0
	v_mfma_f32_16x16x32_bf16 v[104:107], v[92:95], v[200:203], 0
	v_mfma_f32_16x16x32_bf16 v[80:83], v[72:75], v[208:211], 0
	v_mfma_f32_16x16x32_bf16 v[76:79], v[92:95], v[208:211], 0
	v_mfma_f32_16x16x32_bf16 v[140:143], v[84:87], v[188:191], v[140:143]
	v_mfma_f32_16x16x32_bf16 v[136:139], v[96:99], v[188:191], v[136:139]
	v_mfma_f32_16x16x32_bf16 v[124:127], v[84:87], v[196:199], v[124:127]
	v_mfma_f32_16x16x32_bf16 v[120:123], v[96:99], v[196:199], v[120:123]
	v_mfma_f32_16x16x32_bf16 v[108:111], v[84:87], v[204:207], v[108:111]
	v_mfma_f32_16x16x32_bf16 v[104:107], v[96:99], v[204:207], v[104:107]
	v_mfma_f32_16x16x32_bf16 v[80:83], v[84:87], v[212:215], v[80:83]
	v_mfma_f32_16x16x32_bf16 v[76:79], v[96:99], v[212:215], v[76:79]
	s_setprio 0
	s_setprio 1
	v_mfma_f32_16x16x32_bf16 v[132:135], v[156:159], v[182:185], 0
	v_mfma_f32_16x16x32_bf16 v[128:131], v[174:177], v[182:185], 0
	v_mfma_f32_16x16x32_bf16 v[116:119], v[156:159], v[192:195], 0
	v_mfma_f32_16x16x32_bf16 v[112:115], v[174:177], v[192:195], 0
	v_mfma_f32_16x16x32_bf16 v[100:103], v[156:159], v[200:203], 0
	v_mfma_f32_16x16x32_bf16 v[88:91], v[174:177], v[200:203], 0
	v_mfma_f32_16x16x32_bf16 v[68:71], v[156:159], v[208:211], 0
	v_mfma_f32_16x16x32_bf16 v[64:67], v[174:177], v[208:211], 0
	v_mfma_f32_16x16x32_bf16 v[132:135], v[160:163], v[188:191], v[132:135]
	v_mfma_f32_16x16x32_bf16 v[128:131], v[178:181], v[188:191], v[128:131]
	v_mfma_f32_16x16x32_bf16 v[116:119], v[160:163], v[196:199], v[116:119]
	v_mfma_f32_16x16x32_bf16 v[112:115], v[178:181], v[196:199], v[112:115]
	v_mfma_f32_16x16x32_bf16 v[100:103], v[160:163], v[204:207], v[100:103]
	v_mfma_f32_16x16x32_bf16 v[88:91], v[178:181], v[204:207], v[88:91]
	v_mfma_f32_16x16x32_bf16 v[68:71], v[160:163], v[212:215], v[68:71]
	v_mfma_f32_16x16x32_bf16 v[64:67], v[178:181], v[212:215], v[64:67]
	s_barrier
	s_setprio 0
	s_add_i32 s59, s53, s33
	v_lshl_add_u64 v[164:165], s[40:41], 0, v[144:145]
	s_mov_b32 m0, s59
	ds_read_b128 v[182:185], v171 offset:16384
	ds_read_b128 v[188:191], v171 offset:17408
	ds_read_b128 v[192:195], v171 offset:18432
	ds_read_b128 v[196:199], v171 offset:19456
	ds_read_b128 v[200:203], v171 offset:20480
	ds_read_b128 v[204:207], v171 offset:21504
	ds_read_b128 v[208:211], v171 offset:22528
	ds_read_b128 v[212:215], v171 offset:23552
	global_load_lds_dwordx4 v[164:165], off
	s_add_i32 m0, s59, 0x2000
	s_add_u32 s60, s40, 0x80000
	v_lshl_add_u64 v[216:217], s[40:41], 0, v[146:147]
	s_addc_u32 s61, s41, 0
	s_add_i32 s59, s54, s33
	global_load_lds_dwordx4 v[216:217], off
	v_lshl_add_u64 v[218:219], s[60:61], 0, v[144:145]
	s_mov_b32 m0, s59
	v_lshl_add_u64 v[220:221], s[42:43], 0, v[146:147]
	global_load_lds_dwordx4 v[218:219], off
	v_lshl_add_u64 v[218:219], s[60:61], 0, v[146:147]
	s_add_i32 m0, s59, 0x2000
	s_nop 0
	global_load_lds_dwordx4 v[218:219], off
	v_lshl_add_u64 v[218:219], s[42:43], 0, v[144:145]
	s_mov_b32 m0, s37
	s_nop 0
	global_load_lds_dwordx4 v[218:219], off
	s_mov_b32 m0, s44
	s_nop 0
	global_load_lds_dwordx4 v[220:221], off
	s_setprio 1
	s_waitcnt vmcnt(8)
	s_waitcnt lgkmcnt(0)
	s_barrier
; #define PG8_STAGE(bufoff, gbase, voff) do { _Pragma("unroll") for (int _i = 0; _i < 2; ++_i) \
;         __builtin_amdgcn_global_load_lds((const unsigned*)((const char*)(gbase) + (voff)[_i]), (PG8_LAS unsigned*)(lds + (bufoff) + ldsw + _i * 8192), 16, 0, 0); } while (0)
; #define PG8_LDA(dst, b, h) do { _Pragma("unroll") for (int m = 0; m < 4; ++m) _Pragma("unroll") for (int k = 0; k < 2; ++k) dst[m][k] = *(const PG8_LAS bf16x8*)(lds + PG8_SA(b, h) + aoff + m * 2048 + k * 1024); } while (0)
; #define PG8_LDB(dst, b, h) do { _Pragma("unroll") for (int n = 0; n < 2; ++n) _Pragma("unroll") for (int k = 0; k < 2; ++k) dst[n][k] = *(const PG8_LAS bf16x8*)(lds + PG8_SB(b, h) + boff + n * 2048 + k * 1024); } while (0)
; #define PG8_MMA(ai, bj, At, Bt) do { __builtin_amdgcn_s_setprio(1); _Pragma("unroll") for (int m = 0; m < 4; ++m) _Pragma("unroll") for (int n = 0; n < 2; ++n) _Pragma("unroll") for (int k = 0; k < 2; ++k) \
;         acc[ai][bj][m][n] = __builtin_amdgcn_mfma_f32_16x16x32_bf16(Bt[n][k], At[m][k], acc[ai][bj][m][n], 0, 0, 0); __builtin_amdgcn_s_setprio(0); } while (0)
; #define PG8_WAIT_V(n) asm volatile("s_waitcnt vmcnt(" #n ")" ::: "memory")
; #define PG8_WAIT_L(n) asm volatile("s_waitcnt lgkmcnt(" #n ")" ::: "memory")
; #define PG8_BAR __builtin_amdgcn_s_barrier()
; #define PG8_SCHED __builtin_amdgcn_sched_barrier(0)
; template <class Epi, class Sched, bool ALIGN_EPI = false, bool SP2 = false>
; __device__ __forceinline__ void gemm_phase(PG8_LAS unsigned char* lds, const Gemm g, const Sched& S, const Epi& E) {
;     ...
;             PG8_WAIT_V(8); PG8_WAIT_L(0); PG8_BAR; PG8_MMA(1, 0, At, B0); PG8_MMA(1, 1, At, B1); PG8_BAR; PG8_SCHED;
;             PG8_LDB(B0, 1, 0); PG8_LDB(B1, 1, 1); PG8_SCHED; PG8_LDA(At, 1, 0); PG8_STAGE(PG8_SA(0, 1), a2 + hstep, voffA);
;             PG8_WAIT_V(8); PG8_WAIT_L(0); PG8_BAR; PG8_MMA(0, 0, At, B0); PG8_MMA(0, 1, At, B1); PG8_BAR; PG8_SCHED;
;             PG8_LDA(At, 1, 1); PG8_STAGE(PG8_SB(1, 0), b3, voffB); PG8_STAGE(PG8_SB(1, 1), b3 + hstep, voffB); PG8_STAGE(PG8_SA(1, 0), a3, voffA);
	v_mfma_f32_16x16x32_bf16 v[60:63], v[72:75], v[182:185], 0
	v_mfma_f32_16x16x32_bf16 v[56:59], v[92:95], v[182:185], 0
	v_mfma_f32_16x16x32_bf16 v[44:47], v[72:75], v[192:195], 0
	v_mfma_f32_16x16x32_bf16 v[40:43], v[92:95], v[192:195], 0
	v_mfma_f32_16x16x32_bf16 v[28:31], v[72:75], v[200:203], 0
	v_mfma_f32_16x16x32_bf16 v[24:27], v[92:95], v[200:203], 0
	v_mfma_f32_16x16x32_bf16 v[12:15], v[72:75], v[208:211], 0
	v_mfma_f32_16x16x32_bf16 v[8:11], v[92:95], v[208:211], 0
	v_mfma_f32_16x16x32_bf16 v[60:63], v[84:87], v[188:191], v[60:63]
	v_mfma_f32_16x16x32_bf16 v[56:59], v[96:99], v[188:191], v[56:59]
	v_mfma_f32_16x16x32_bf16 v[44:47], v[84:87], v[196:199], v[44:47]
	v_mfma_f32_16x16x32_bf16 v[40:43], v[96:99], v[196:199], v[40:43]
	v_mfma_f32_16x16x32_bf16 v[28:31], v[84:87], v[204:207], v[28:31]
	v_mfma_f32_16x16x32_bf16 v[24:27], v[96:99], v[204:207], v[24:27]
	v_mfma_f32_16x16x32_bf16 v[12:15], v[84:87], v[212:215], v[12:15]
	v_mfma_f32_16x16x32_bf16 v[8:11], v[96:99], v[212:215], v[8:11]
	s_setprio 0
	s_setprio 1
	v_mfma_f32_16x16x32_bf16 v[52:55], v[156:159], v[182:185], 0
	v_mfma_f32_16x16x32_bf16 v[48:51], v[174:177], v[182:185], 0
	v_mfma_f32_16x16x32_bf16 v[36:39], v[156:159], v[192:195], 0
	v_mfma_f32_16x16x32_bf16 v[32:35], v[174:177], v[192:195], 0
	v_mfma_f32_16x16x32_bf16 v[20:23], v[156:159], v[200:203], 0
	v_mfma_f32_16x16x32_bf16 v[16:19], v[174:177], v[200:203], 0
	v_mfma_f32_16x16x32_bf16 v[4:7], v[156:159], v[208:211], 0
	v_mfma_f32_16x16x32_bf16 v[0:3], v[174:177], v[208:211], 0
	v_mfma_f32_16x16x32_bf16 v[52:55], v[160:163], v[188:191], v[52:55]
	v_mfma_f32_16x16x32_bf16 v[48:51], v[178:181], v[188:191], v[48:51]
	v_mfma_f32_16x16x32_bf16 v[36:39], v[160:163], v[196:199], v[36:39]
	v_mfma_f32_16x16x32_bf16 v[32:35], v[178:181], v[196:199], v[32:35]
	v_mfma_f32_16x16x32_bf16 v[20:23], v[160:163], v[204:207], v[20:23]
	v_mfma_f32_16x16x32_bf16 v[16:19], v[178:181], v[204:207], v[16:19]
	v_mfma_f32_16x16x32_bf16 v[4:7], v[160:163], v[212:215], v[4:7]
	v_mfma_f32_16x16x32_bf16 v[0:3], v[178:181], v[212:215], v[0:3]
	s_barrier
	s_setprio 0
	s_add_i32 s59, 0, 0x18000
	s_add_i32 s60, 0, 0x1c000
	v_add_u32_e32 v96, s59, v167
	v_add_u32_e32 v173, s60, v167
	ds_read_b128 v[72:75], v96
	ds_read_b128 v[84:87], v96 offset:1024
	ds_read_b128 v[92:95], v96 offset:2048
	ds_read_b128 v[96:99], v96 offset:3072
	ds_read_b128 v[156:159], v173
	ds_read_b128 v[160:163], v173 offset:1024
	ds_read_b128 v[174:177], v173 offset:2048
	ds_read_b128 v[178:181], v173 offset:3072
	s_add_u32 s42, s42, 0x80000
	s_addc_u32 s43, s43, 0
	s_mov_b32 m0, s45
	v_lshl_add_u64 v[222:223], s[42:43], 0, v[144:145]
	ds_read_b128 v[182:185], v171 offset:32768
	ds_read_b128 v[188:191], v171 offset:33792
	ds_read_b128 v[192:195], v171 offset:34816
	ds_read_b128 v[196:199], v171 offset:35840
	ds_read_b128 v[200:203], v171 offset:36864
	ds_read_b128 v[204:207], v171 offset:37888
	ds_read_b128 v[208:211], v171 offset:38912
	ds_read_b128 v[212:215], v171 offset:39936
	global_load_lds_dwordx4 v[222:223], off
	v_lshl_add_u64 v[222:223], s[42:43], 0, v[146:147]
	s_mov_b32 m0, s46
	s_nop 0
	global_load_lds_dwordx4 v[222:223], off
	s_setprio 1
	s_waitcnt vmcnt(8)
	s_waitcnt lgkmcnt(0)
	s_barrier
	v_mfma_f32_16x16x32_bf16 v[140:143], v[72:75], v[182:185], v[140:143]
	v_mfma_f32_16x16x32_bf16 v[136:139], v[92:95], v[182:185], v[136:139]
	v_mfma_f32_16x16x32_bf16 v[124:127], v[72:75], v[192:195], v[124:127]
	v_mfma_f32_16x16x32_bf16 v[120:123], v[92:95], v[192:195], v[120:123]
	v_mfma_f32_16x16x32_bf16 v[108:111], v[72:75], v[200:203], v[108:111]
	v_mfma_f32_16x16x32_bf16 v[104:107], v[92:95], v[200:203], v[104:107]
	v_mfma_f32_16x16x32_bf16 v[80:83], v[72:75], v[208:211], v[80:83]
	v_mfma_f32_16x16x32_bf16 v[76:79], v[92:95], v[208:211], v[76:79]
	v_mfma_f32_16x16x32_bf16 v[140:143], v[84:87], v[188:191], v[140:143]
	v_mfma_f32_16x16x32_bf16 v[136:139], v[96:99], v[188:191], v[136:139]
	v_mfma_f32_16x16x32_bf16 v[124:127], v[84:87], v[196:199], v[124:127]
	v_mfma_f32_16x16x32_bf16 v[120:123], v[96:99], v[196:199], v[120:123]
	v_mfma_f32_16x16x32_bf16 v[108:111], v[84:87], v[204:207], v[108:111]
	v_mfma_f32_16x16x32_bf16 v[104:107], v[96:99], v[204:207], v[104:107]
	v_mfma_f32_16x16x32_bf16 v[80:83], v[84:87], v[212:215], v[80:83]
	v_mfma_f32_16x16x32_bf16 v[76:79], v[96:99], v[212:215], v[76:79]
	s_setprio 0
	s_setprio 1
	v_mfma_f32_16x16x32_bf16 v[132:135], v[156:159], v[182:185], v[132:135]
	v_mfma_f32_16x16x32_bf16 v[128:131], v[174:177], v[182:185], v[128:131]
	v_mfma_f32_16x16x32_bf16 v[116:119], v[156:159], v[192:195], v[116:119]
	v_mfma_f32_16x16x32_bf16 v[112:115], v[174:177], v[192:195], v[112:115]
	v_mfma_f32_16x16x32_bf16 v[100:103], v[156:159], v[200:203], v[100:103]
	v_mfma_f32_16x16x32_bf16 v[88:91], v[174:177], v[200:203], v[88:91]
	v_mfma_f32_16x16x32_bf16 v[68:71], v[156:159], v[208:211], v[68:71]
	v_mfma_f32_16x16x32_bf16 v[64:67], v[174:177], v[208:211], v[64:67]
	v_mfma_f32_16x16x32_bf16 v[132:135], v[160:163], v[188:191], v[132:135]
	v_mfma_f32_16x16x32_bf16 v[128:131], v[178:181], v[188:191], v[128:131]
	v_mfma_f32_16x16x32_bf16 v[116:119], v[160:163], v[196:199], v[116:119]
	v_mfma_f32_16x16x32_bf16 v[112:115], v[178:181], v[196:199], v[112:115]
	v_mfma_f32_16x16x32_bf16 v[100:103], v[160:163], v[204:207], v[100:103]
	v_mfma_f32_16x16x32_bf16 v[88:91], v[178:181], v[204:207], v[88:91]
	v_mfma_f32_16x16x32_bf16 v[68:71], v[160:163], v[212:215], v[68:71]
	v_mfma_f32_16x16x32_bf16 v[64:67], v[178:181], v[212:215], v[64:67]
	s_barrier
; #define PG8_STAGE(bufoff, gbase, voff) do { _Pragma("unroll") for (int _i = 0; _i < 2; ++_i) \
;         __builtin_amdgcn_global_load_lds((const unsigned*)((const char*)(gbase) + (voff)[_i]), (PG8_LAS unsigned*)(lds + (bufoff) + ldsw + _i * 8192), 16, 0, 0); } while (0)
; #define PG8_LDA(dst, b, h) do { _Pragma("unroll") for (int m = 0; m < 4; ++m) _Pragma("unroll") for (int k = 0; k < 2; ++k) dst[m][k] = *(const PG8_LAS bf16x8*)(lds + PG8_SA(b, h) + aoff + m * 2048 + k * 1024); } while (0)
; #define PG8_MMA(ai, bj, At, Bt) do { __builtin_amdgcn_s_setprio(1); _Pragma("unroll") for (int m = 0; m < 4; ++m) _Pragma("unroll") for (int n = 0; n < 2; ++n) _Pragma("unroll") for (int k = 0; k < 2; ++k) \
;         acc[ai][bj][m][n] = __builtin_amdgcn_mfma_f32_16x16x32_bf16(Bt[n][k], At[m][k], acc[ai][bj][m][n], 0, 0, 0); __builtin_amdgcn_s_setprio(0); } while (0)
; #define PG8_WAIT_V(n) asm volatile("s_waitcnt vmcnt(" #n ")" ::: "memory")
; #define PG8_WAIT_L(n) asm volatile("s_waitcnt lgkmcnt(" #n ")" ::: "memory")
; #define PG8_BAR __builtin_amdgcn_s_barrier()
; #define PG8_SCHED __builtin_amdgcn_sched_barrier(0)
; template <class Epi, class Sched, bool ALIGN_EPI = false, bool SP2 = false>
; __device__ __forceinline__ void gemm_phase(PG8_LAS unsigned char* lds, const Gemm g, const Sched& S, const Epi& E) {
;     ...
;             PG8_LDA(At, 1, 1); PG8_STAGE(PG8_SB(1, 0), b3, voffB); PG8_STAGE(PG8_SB(1, 1), b3 + hstep, voffB); PG8_STAGE(PG8_SA(1, 0), a3, voffA);
;             PG8_WAIT_V(8); PG8_WAIT_L(0); PG8_BAR; PG8_MMA(1, 0, At, B0); PG8_MMA(1, 1, At, B1); PG8_BAR; PG8_SCHED;
	s_setprio 0
	s_add_i32 s42, s59, s33
	v_lshl_add_u64 v[164:165], v[164:165], 0, s[12:13]
	s_mov_b32 m0, s42
	ds_read_b128 v[182:185], v171 offset:49152
	ds_read_b128 v[188:191], v171 offset:50176
	ds_read_b128 v[192:195], v171 offset:51200
	ds_read_b128 v[196:199], v171 offset:52224
	ds_read_b128 v[200:203], v171 offset:53248
	ds_read_b128 v[204:207], v171 offset:54272
	ds_read_b128 v[208:211], v171 offset:55296
	ds_read_b128 v[212:215], v171 offset:56320
	global_load_lds_dwordx4 v[164:165], off
	s_add_i32 m0, s42, 0x2000
	s_add_u32 s40, s40, 0x80080
	v_lshl_add_u64 v[164:165], v[216:217], 0, s[12:13]
	s_addc_u32 s41, s41, 0
	s_add_i32 s42, s60, s33
	global_load_lds_dwordx4 v[164:165], off
	v_lshl_add_u64 v[164:165], s[40:41], 0, v[144:145]
	s_mov_b32 m0, s42
	s_nop 0
	global_load_lds_dwordx4 v[164:165], off
	v_lshl_add_u64 v[164:165], s[40:41], 0, v[146:147]
	s_add_i32 m0, s42, 0x2000
	s_nop 0
	global_load_lds_dwordx4 v[164:165], off
	v_lshl_add_u64 v[164:165], v[218:219], 0, s[12:13]
	s_mov_b32 m0, s50
	s_nop 0
	global_load_lds_dwordx4 v[164:165], off
	v_lshl_add_u64 v[164:165], v[220:221], 0, s[12:13]
	s_mov_b32 m0, s51
	s_nop 0
	global_load_lds_dwordx4 v[164:165], off
	s_setprio 1
	s_waitcnt vmcnt(8)
	s_waitcnt lgkmcnt(0)
	s_barrier
	v_mfma_f32_16x16x32_bf16 v[60:63], v[72:75], v[182:185], v[60:63]
	v_mfma_f32_16x16x32_bf16 v[56:59], v[92:95], v[182:185], v[56:59]
	v_mfma_f32_16x16x32_bf16 v[44:47], v[72:75], v[192:195], v[44:47]
	v_mfma_f32_16x16x32_bf16 v[40:43], v[92:95], v[192:195], v[40:43]
	v_mfma_f32_16x16x32_bf16 v[28:31], v[72:75], v[200:203], v[28:31]
	v_mfma_f32_16x16x32_bf16 v[24:27], v[92:95], v[200:203], v[24:27]
	v_mfma_f32_16x16x32_bf16 v[12:15], v[72:75], v[208:211], v[12:15]
	v_mfma_f32_16x16x32_bf16 v[8:11], v[92:95], v[208:211], v[8:11]
	v_mfma_f32_16x16x32_bf16 v[60:63], v[84:87], v[188:191], v[60:63]
	v_mfma_f32_16x16x32_bf16 v[56:59], v[96:99], v[188:191], v[56:59]
	v_mfma_f32_16x16x32_bf16 v[44:47], v[84:87], v[196:199], v[44:47]
	v_mfma_f32_16x16x32_bf16 v[40:43], v[96:99], v[196:199], v[40:43]
	v_mfma_f32_16x16x32_bf16 v[28:31], v[84:87], v[204:207], v[28:31]
	v_mfma_f32_16x16x32_bf16 v[24:27], v[96:99], v[204:207], v[24:27]
	v_mfma_f32_16x16x32_bf16 v[12:15], v[84:87], v[212:215], v[12:15]
	v_mfma_f32_16x16x32_bf16 v[8:11], v[96:99], v[212:215], v[8:11]
	s_setprio 0
	s_setprio 1
	v_mfma_f32_16x16x32_bf16 v[52:55], v[156:159], v[182:185], v[52:55]
	v_mfma_f32_16x16x32_bf16 v[48:51], v[174:177], v[182:185], v[48:51]
	v_mfma_f32_16x16x32_bf16 v[36:39], v[156:159], v[192:195], v[36:39]
	v_mfma_f32_16x16x32_bf16 v[32:35], v[174:177], v[192:195], v[32:35]
	v_mfma_f32_16x16x32_bf16 v[20:23], v[156:159], v[200:203], v[20:23]
	v_mfma_f32_16x16x32_bf16 v[16:19], v[174:177], v[200:203], v[16:19]
	v_mfma_f32_16x16x32_bf16 v[4:7], v[156:159], v[208:211], v[4:7]
	v_mfma_f32_16x16x32_bf16 v[0:3], v[174:177], v[208:211], v[0:3]
	v_mfma_f32_16x16x32_bf16 v[52:55], v[160:163], v[188:191], v[52:55]
	v_mfma_f32_16x16x32_bf16 v[48:51], v[178:181], v[188:191], v[48:51]
	v_mfma_f32_16x16x32_bf16 v[36:39], v[160:163], v[196:199], v[36:39]
	v_mfma_f32_16x16x32_bf16 v[32:35], v[178:181], v[196:199], v[32:35]
	v_mfma_f32_16x16x32_bf16 v[20:23], v[160:163], v[204:207], v[20:23]
	v_mfma_f32_16x16x32_bf16 v[16:19], v[178:181], v[204:207], v[16:19]
	v_mfma_f32_16x16x32_bf16 v[4:7], v[160:163], v[212:215], v[4:7]
	v_mfma_f32_16x16x32_bf16 v[0:3], v[178:181], v[212:215], v[0:3]
	s_barrier
	s_setprio 0
	s_add_i32 s58, s58, 2
	s_add_u32 s38, s38, 0x100
	s_addc_u32 s39, s39, 0
	s_add_u32 s56, s56, 0x100
	s_addc_u32 s57, s57, 0
	s_cmp_gt_u32 s58, 29
	.p2align	6

;     __device__ __forceinline__ bool next(int i, Unit& u) const { if (!base.next(i >> 1, u)) return false; if (i & 1) { u.pm += 64; u.pn += 8; } return true; }
; #define PG8_STAGE(bufoff, gbase, voff) do { _Pragma("unroll") for (int _i = 0; _i < 2; ++_i) \
;         __builtin_amdgcn_global_load_lds((const unsigned*)((const char*)(gbase) + (voff)[_i]), (PG8_LAS unsigned*)(lds + (bufoff) + ldsw + _i * 8192), 16, 0, 0); } while (0)
; #define PG8_LDA(dst, b, h) do { _Pragma("unroll") for (int m = 0; m < 4; ++m) _Pragma("unroll") for (int k = 0; k < 2; ++k) dst[m][k] = *(const PG8_LAS bf16x8*)(lds + PG8_SA(b, h) + aoff + m * 2048 + k * 1024); } while (0)
; #define PG8_LDB(dst, b, h) do { _Pragma("unroll") for (int n = 0; n < 2; ++n) _Pragma("unroll") for (int k = 0; k < 2; ++k) dst[n][k] = *(const PG8_LAS bf16x8*)(lds + PG8_SB(b, h) + boff + n * 2048 + k * 1024); } while (0)
; #define PG8_WAIT_V(n) asm volatile("s_waitcnt vmcnt(" #n ")" ::: "memory")
; #define PG8_WAIT_L(n) asm volatile("s_waitcnt lgkmcnt(" #n ")" ::: "memory")
; #define PG8_BAR __builtin_amdgcn_s_barrier()
; #define PG8_SCHED __builtin_amdgcn_sched_barrier(0)
; template <class Epi, class Sched, bool ALIGN_EPI = false, bool SP2 = false>
; __device__ __forceinline__ void gemm_phase(PG8_LAS unsigned char* lds, const Gemm g, const Sched& S, const Epi& E) {
;     ...
;         const bool has_next = S.next(ui + 1, nxt);
;         const char* nA = has_next ? (const char*)g.A + (size_t)nxt.pm * tstep : cA; const char* nB = has_next ? (const char*)g.Bt + (size_t)nxt.pn * tstep : cB;
;         for (int t = 0; t < nt; t += 2) {
;             const bool last = (t == nt - 2);
;             const char* a1 = cA + (size_t)(t + 1) * kstep;
;             const char* a2 = last ? nA : cA + (size_t)(t + 2) * kstep; const char* b2 = last ? nB : cB + (size_t)(t + 2) * kstep;
;             const char* a3 = a2 + kstep; const char* b3 = b2 + kstep;
;             if (last && has_next) S.a_ready(nxt);
;             if constexpr (SP2) {
;             PG8_LDB(B0, 0, 0); PG8_LDB(B1, 0, 1); PG8_SCHED; PG8_LDA(At, 0, 0); PG8_STAGE(PG8_SA(1, 1), a1 + hstep, voffA);
;             PG8_WAIT_V(8); PG8_WAIT_L(0); PG8_BAR; PG8_MMA(0, 0, At, B0); PG8_MMA(0, 1, At, B1); PG8_BAR; PG8_SCHED;
;             PG8_LDA(At, 0, 1); PG8_STAGE(PG8_SB(0, 0), b2, voffB); PG8_STAGE(PG8_SB(0, 1), b2 + hstep, voffB); PG8_STAGE(PG8_SA(0, 0), a2, voffA);
.LBB0_993:
	s_ashr_i32 s15, s14, 31
	s_lshl_b64 s[18:19], s[14:15], 20
	s_add_u32 s18, s8, s18
	s_addc_u32 s19, s9, s19
	s_and_b64 s[20:21], s[4:5], exec
	s_cselect_b32 s15, s19, s25
	s_cselect_b32 s43, s18, s24
	s_ashr_i32 s17, s16, 31
	s_lshl_b64 s[20:21], s[16:17], 20
	v_readlane_b32 s28, v236, 52
	v_readlane_b32 s29, v236, 53
	s_add_u32 s20, s28, s20
	s_addc_u32 s21, s29, s21
	s_and_b64 s[28:29], s[4:5], exec
	s_cselect_b32 s17, s21, s27
	s_cselect_b32 s44, s20, s26
	s_add_u32 s24, s24, 0x80080
	s_addc_u32 s25, s25, 0
	s_add_u32 s45, s26, 0x100
	s_addc_u32 s46, s27, 0
	s_mov_b32 s47, -2
	ds_read_b128 v[128:131], v173
	ds_read_b128 v[132:135], v173 offset:1024
	ds_read_b128 v[136:139], v173 offset:2048
	ds_read_b128 v[140:143], v173 offset:3072
	ds_read_b128 v[176:179], v174
	ds_read_b128 v[180:183], v174 offset:1024
	ds_read_b128 v[188:191], v174 offset:2048
	ds_read_b128 v[192:195], v174 offset:3072
	s_add_u32 s26, s24, 0xfff80080
	s_addc_u32 s27, s25, -1
	s_cmp_eq_u32 s47, 28
	s_cselect_b32 s29, s15, s27
	s_cselect_b32 s28, s43, s26
	s_cselect_b32 s27, s17, s46
	s_cselect_b32 s26, s44, s45
	v_lshl_add_u64 v[160:161], s[24:25], 0, v[152:153]
	s_add_i32 m0, s23, 0xc000
	ds_read_b128 v[196:199], v175
	ds_read_b128 v[200:203], v175 offset:1024
	ds_read_b128 v[204:207], v175 offset:2048
	ds_read_b128 v[208:211], v175 offset:3072
	ds_read_b128 v[212:215], v175 offset:4096
	ds_read_b128 v[216:219], v175 offset:5120
	ds_read_b128 v[220:223], v175 offset:6144
	ds_read_b128 v[224:227], v175 offset:7168
	global_load_lds_dwordx4 v[160:161], off
	v_lshl_add_u64 v[160:161], s[24:25], 0, v[154:155]
	s_add_i32 m0, s23, 0xe000
	s_nop 0
	global_load_lds_dwordx4 v[160:161], off
	s_setprio 1
	s_waitcnt vmcnt(8)
	s_waitcnt lgkmcnt(0)
	s_barrier
	v_mfma_f32_16x16x32_bf16 v[124:127], v[128:131], v[196:199], 0
	v_mfma_f32_16x16x32_bf16 v[120:123], v[136:139], v[196:199], 0
	v_mfma_f32_16x16x32_bf16 v[108:111], v[128:131], v[204:207], 0
	v_mfma_f32_16x16x32_bf16 v[104:107], v[136:139], v[204:207], 0
	v_mfma_f32_16x16x32_bf16 v[92:95], v[128:131], v[212:215], 0
	v_mfma_f32_16x16x32_bf16 v[88:91], v[136:139], v[212:215], 0
	v_mfma_f32_16x16x32_bf16 v[76:79], v[128:131], v[220:223], 0
	v_mfma_f32_16x16x32_bf16 v[72:75], v[136:139], v[220:223], 0
	v_mfma_f32_16x16x32_bf16 v[124:127], v[132:135], v[200:203], v[124:127]
	v_mfma_f32_16x16x32_bf16 v[120:123], v[140:143], v[200:203], v[120:123]
	v_mfma_f32_16x16x32_bf16 v[108:111], v[132:135], v[208:211], v[108:111]
	v_mfma_f32_16x16x32_bf16 v[104:107], v[140:143], v[208:211], v[104:107]
	v_mfma_f32_16x16x32_bf16 v[92:95], v[132:135], v[216:219], v[92:95]
	v_mfma_f32_16x16x32_bf16 v[88:91], v[140:143], v[216:219], v[88:91]
	v_mfma_f32_16x16x32_bf16 v[76:79], v[132:135], v[224:227], v[76:79]
	v_mfma_f32_16x16x32_bf16 v[72:75], v[140:143], v[224:227], v[72:75]
	s_setprio 0
	s_setprio 1
	v_mfma_f32_16x16x32_bf16 v[116:119], v[176:179], v[196:199], 0
	v_mfma_f32_16x16x32_bf16 v[112:115], v[188:191], v[196:199], 0
	v_mfma_f32_16x16x32_bf16 v[100:103], v[176:179], v[204:207], 0
	v_mfma_f32_16x16x32_bf16 v[96:99], v[188:191], v[204:207], 0
	v_mfma_f32_16x16x32_bf16 v[84:87], v[176:179], v[212:215], 0
	v_mfma_f32_16x16x32_bf16 v[80:83], v[188:191], v[212:215], 0
	v_mfma_f32_16x16x32_bf16 v[68:71], v[176:179], v[220:223], 0
	v_mfma_f32_16x16x32_bf16 v[64:67], v[188:191], v[220:223], 0
	v_mfma_f32_16x16x32_bf16 v[116:119], v[180:183], v[200:203], v[116:119]
	v_mfma_f32_16x16x32_bf16 v[112:115], v[192:195], v[200:203], v[112:115]
	v_mfma_f32_16x16x32_bf16 v[100:103], v[180:183], v[208:211], v[100:103]
	v_mfma_f32_16x16x32_bf16 v[96:99], v[192:195], v[208:211], v[96:99]
	v_mfma_f32_16x16x32_bf16 v[84:87], v[180:183], v[216:219], v[84:87]
	v_mfma_f32_16x16x32_bf16 v[80:83], v[192:195], v[216:219], v[80:83]
	v_mfma_f32_16x16x32_bf16 v[68:71], v[180:183], v[224:227], v[68:71]
	v_mfma_f32_16x16x32_bf16 v[64:67], v[192:195], v[224:227], v[64:67]
	s_barrier
	s_setprio 0
	s_add_i32 s48, s40, s31
	v_lshl_add_u64 v[160:161], s[26:27], 0, v[146:147]
	s_mov_b32 m0, s48
	ds_read_b128 v[196:199], v175 offset:16384
	ds_read_b128 v[200:203], v175 offset:17408
	ds_read_b128 v[204:207], v175 offset:18432
	ds_read_b128 v[208:211], v175 offset:19456
	ds_read_b128 v[212:215], v175 offset:20480
	ds_read_b128 v[216:219], v175 offset:21504
	ds_read_b128 v[220:223], v175 offset:22528
	ds_read_b128 v[224:227], v175 offset:23552
	global_load_lds_dwordx4 v[160:161], off
	s_add_i32 m0, s48, 0x2000
	s_add_u32 s48, s26, 0x80000
	v_lshl_add_u64 v[184:185], s[26:27], 0, v[150:151]
	s_addc_u32 s49, s27, 0
	s_add_i32 s50, s41, s31
	global_load_lds_dwordx4 v[184:185], off
	v_lshl_add_u64 v[228:229], s[48:49], 0, v[146:147]
	s_mov_b32 m0, s50
	v_lshl_add_u64 v[230:231], s[28:29], 0, v[148:149]
	global_load_lds_dwordx4 v[228:229], off
	v_lshl_add_u64 v[228:229], s[48:49], 0, v[150:151]
	s_add_i32 m0, s50, 0x2000
	s_nop 0
	global_load_lds_dwordx4 v[228:229], off
	v_lshl_add_u64 v[228:229], s[28:29], 0, v[144:145]
	s_mov_b32 m0, s23
	s_nop 0
	global_load_lds_dwordx4 v[228:229], off
	s_mov_b32 m0, s33
	s_nop 0
	global_load_lds_dwordx4 v[230:231], off
	s_setprio 1
	s_waitcnt vmcnt(8)
	s_waitcnt lgkmcnt(0)
	s_barrier
; #define PG8_STAGE(bufoff, gbase, voff) do { _Pragma("unroll") for (int _i = 0; _i < 2; ++_i) \
;         __builtin_amdgcn_global_load_lds((const unsigned*)((const char*)(gbase) + (voff)[_i]), (PG8_LAS unsigned*)(lds + (bufoff) + ldsw + _i * 8192), 16, 0, 0); } while (0)
; #define PG8_LDA(dst, b, h) do { _Pragma("unroll") for (int m = 0; m < 4; ++m) _Pragma("unroll") for (int k = 0; k < 2; ++k) dst[m][k] = *(const PG8_LAS bf16x8*)(lds + PG8_SA(b, h) + aoff + m * 2048 + k * 1024); } while (0)
; #define PG8_LDB(dst, b, h) do { _Pragma("unroll") for (int n = 0; n < 2; ++n) _Pragma("unroll") for (int k = 0; k < 2; ++k) dst[n][k] = *(const PG8_LAS bf16x8*)(lds + PG8_SB(b, h) + boff + n * 2048 + k * 1024); } while (0)
; #define PG8_MMA(ai, bj, At, Bt) do { __builtin_amdgcn_s_setprio(1); _Pragma("unroll") for (int m = 0; m < 4; ++m) _Pragma("unroll") for (int n = 0; n < 2; ++n) _Pragma("unroll") for (int k = 0; k < 2; ++k) \
;         acc[ai][bj][m][n] = __builtin_amdgcn_mfma_f32_16x16x32_bf16(Bt[n][k], At[m][k], acc[ai][bj][m][n], 0, 0, 0); __builtin_amdgcn_s_setprio(0); } while (0)
; #define PG8_WAIT_V(n) asm volatile("s_waitcnt vmcnt(" #n ")" ::: "memory")
; #define PG8_WAIT_L(n) asm volatile("s_waitcnt lgkmcnt(" #n ")" ::: "memory")
; #define PG8_BAR __builtin_amdgcn_s_barrier()
; #define PG8_SCHED __builtin_amdgcn_sched_barrier(0)
; template <class Epi, class Sched, bool ALIGN_EPI = false, bool SP2 = false>
; __device__ __forceinline__ void gemm_phase(PG8_LAS unsigned char* lds, const Gemm g, const Sched& S, const Epi& E) {
;     ...
;             PG8_WAIT_V(8); PG8_WAIT_L(0); PG8_BAR; PG8_MMA(1, 0, At, B0); PG8_MMA(1, 1, At, B1); PG8_BAR; PG8_SCHED;
;             PG8_LDB(B0, 1, 0); PG8_LDB(B1, 1, 1); PG8_SCHED; PG8_LDA(At, 1, 0); PG8_STAGE(PG8_SA(0, 1), a2 + hstep, voffA);
;             PG8_WAIT_V(8); PG8_WAIT_L(0); PG8_BAR; PG8_MMA(0, 0, At, B0); PG8_MMA(0, 1, At, B1); PG8_BAR; PG8_SCHED;
;             PG8_LDA(At, 1, 1); PG8_STAGE(PG8_SB(1, 0), b3, voffB); PG8_STAGE(PG8_SB(1, 1), b3 + hstep, voffB); PG8_STAGE(PG8_SA(1, 0), a3, voffA);
	v_mfma_f32_16x16x32_bf16 v[60:63], v[128:131], v[196:199], 0
	v_mfma_f32_16x16x32_bf16 v[56:59], v[136:139], v[196:199], 0
	v_mfma_f32_16x16x32_bf16 v[44:47], v[128:131], v[204:207], 0
	v_mfma_f32_16x16x32_bf16 v[40:43], v[136:139], v[204:207], 0
	v_mfma_f32_16x16x32_bf16 v[28:31], v[128:131], v[212:215], 0
	v_mfma_f32_16x16x32_bf16 v[24:27], v[136:139], v[212:215], 0
	v_mfma_f32_16x16x32_bf16 v[12:15], v[128:131], v[220:223], 0
	v_mfma_f32_16x16x32_bf16 v[8:11], v[136:139], v[220:223], 0
	v_mfma_f32_16x16x32_bf16 v[60:63], v[132:135], v[200:203], v[60:63]
	v_mfma_f32_16x16x32_bf16 v[56:59], v[140:143], v[200:203], v[56:59]
	v_mfma_f32_16x16x32_bf16 v[44:47], v[132:135], v[208:211], v[44:47]
	v_mfma_f32_16x16x32_bf16 v[40:43], v[140:143], v[208:211], v[40:43]
	v_mfma_f32_16x16x32_bf16 v[28:31], v[132:135], v[216:219], v[28:31]
	v_mfma_f32_16x16x32_bf16 v[24:27], v[140:143], v[216:219], v[24:27]
	v_mfma_f32_16x16x32_bf16 v[12:15], v[132:135], v[224:227], v[12:15]
	v_mfma_f32_16x16x32_bf16 v[8:11], v[140:143], v[224:227], v[8:11]
	s_setprio 0
	s_setprio 1
	v_mfma_f32_16x16x32_bf16 v[52:55], v[176:179], v[196:199], 0
	v_mfma_f32_16x16x32_bf16 v[48:51], v[188:191], v[196:199], 0
	v_mfma_f32_16x16x32_bf16 v[36:39], v[176:179], v[204:207], 0
	v_mfma_f32_16x16x32_bf16 v[32:35], v[188:191], v[204:207], 0
	v_mfma_f32_16x16x32_bf16 v[20:23], v[176:179], v[212:215], 0
	v_mfma_f32_16x16x32_bf16 v[16:19], v[188:191], v[212:215], 0
	v_mfma_f32_16x16x32_bf16 v[4:7], v[176:179], v[220:223], 0
	v_mfma_f32_16x16x32_bf16 v[0:3], v[188:191], v[220:223], 0
	v_mfma_f32_16x16x32_bf16 v[52:55], v[180:183], v[200:203], v[52:55]
	v_mfma_f32_16x16x32_bf16 v[48:51], v[192:195], v[200:203], v[48:51]
	v_mfma_f32_16x16x32_bf16 v[36:39], v[180:183], v[208:211], v[36:39]
	v_mfma_f32_16x16x32_bf16 v[32:35], v[192:195], v[208:211], v[32:35]
	v_mfma_f32_16x16x32_bf16 v[20:23], v[180:183], v[216:219], v[20:23]
	v_mfma_f32_16x16x32_bf16 v[16:19], v[192:195], v[216:219], v[16:19]
	v_mfma_f32_16x16x32_bf16 v[4:7], v[180:183], v[224:227], v[4:7]
	v_mfma_f32_16x16x32_bf16 v[0:3], v[192:195], v[224:227], v[0:3]
	s_barrier
	s_setprio 0
	s_add_i32 s48, 0, 0x18000
	s_add_i32 s49, 0, 0x1c000
	v_add_u32_e32 v140, s48, v163
	v_add_u32_e32 v187, s49, v163
	ds_read_b128 v[128:131], v140
	ds_read_b128 v[132:135], v140 offset:1024
	ds_read_b128 v[136:139], v140 offset:2048
	ds_read_b128 v[140:143], v140 offset:3072
	ds_read_b128 v[176:179], v187
	ds_read_b128 v[180:183], v187 offset:1024
	ds_read_b128 v[188:191], v187 offset:2048
	ds_read_b128 v[192:195], v187 offset:3072
	s_add_u32 s28, s28, 0x80000
	s_addc_u32 s29, s29, 0
	s_mov_b32 m0, s34
	v_lshl_add_u64 v[232:233], s[28:29], 0, v[144:145]
	ds_read_b128 v[196:199], v175 offset:32768
	ds_read_b128 v[200:203], v175 offset:33792
	ds_read_b128 v[204:207], v175 offset:34816
	ds_read_b128 v[208:211], v175 offset:35840
	ds_read_b128 v[212:215], v175 offset:36864
	ds_read_b128 v[216:219], v175 offset:37888
	ds_read_b128 v[220:223], v175 offset:38912
	ds_read_b128 v[224:227], v175 offset:39936
	global_load_lds_dwordx4 v[232:233], off
	v_lshl_add_u64 v[232:233], s[28:29], 0, v[148:149]
	s_mov_b32 m0, s35
	s_nop 0
	global_load_lds_dwordx4 v[232:233], off
	s_setprio 1
	s_waitcnt vmcnt(8)
	s_waitcnt lgkmcnt(0)
	s_barrier
	v_mfma_f32_16x16x32_bf16 v[124:127], v[128:131], v[196:199], v[124:127]
	v_mfma_f32_16x16x32_bf16 v[120:123], v[136:139], v[196:199], v[120:123]
	v_mfma_f32_16x16x32_bf16 v[108:111], v[128:131], v[204:207], v[108:111]
	v_mfma_f32_16x16x32_bf16 v[104:107], v[136:139], v[204:207], v[104:107]
	v_mfma_f32_16x16x32_bf16 v[92:95], v[128:131], v[212:215], v[92:95]
	v_mfma_f32_16x16x32_bf16 v[88:91], v[136:139], v[212:215], v[88:91]
	v_mfma_f32_16x16x32_bf16 v[76:79], v[128:131], v[220:223], v[76:79]
	v_mfma_f32_16x16x32_bf16 v[72:75], v[136:139], v[220:223], v[72:75]
	v_mfma_f32_16x16x32_bf16 v[124:127], v[132:135], v[200:203], v[124:127]
	v_mfma_f32_16x16x32_bf16 v[120:123], v[140:143], v[200:203], v[120:123]
	v_mfma_f32_16x16x32_bf16 v[108:111], v[132:135], v[208:211], v[108:111]
	v_mfma_f32_16x16x32_bf16 v[104:107], v[140:143], v[208:211], v[104:107]
	v_mfma_f32_16x16x32_bf16 v[92:95], v[132:135], v[216:219], v[92:95]
	v_mfma_f32_16x16x32_bf16 v[88:91], v[140:143], v[216:219], v[88:91]
	v_mfma_f32_16x16x32_bf16 v[76:79], v[132:135], v[224:227], v[76:79]
	v_mfma_f32_16x16x32_bf16 v[72:75], v[140:143], v[224:227], v[72:75]
	s_setprio 0
	s_setprio 1
	v_mfma_f32_16x16x32_bf16 v[116:119], v[176:179], v[196:199], v[116:119]
	v_mfma_f32_16x16x32_bf16 v[112:115], v[188:191], v[196:199], v[112:115]
	v_mfma_f32_16x16x32_bf16 v[100:103], v[176:179], v[204:207], v[100:103]
	v_mfma_f32_16x16x32_bf16 v[96:99], v[188:191], v[204:207], v[96:99]
	v_mfma_f32_16x16x32_bf16 v[84:87], v[176:179], v[212:215], v[84:87]
	v_mfma_f32_16x16x32_bf16 v[80:83], v[188:191], v[212:215], v[80:83]
	v_mfma_f32_16x16x32_bf16 v[68:71], v[176:179], v[220:223], v[68:71]
	v_mfma_f32_16x16x32_bf16 v[64:67], v[188:191], v[220:223], v[64:67]
	v_mfma_f32_16x16x32_bf16 v[116:119], v[180:183], v[200:203], v[116:119]
	v_mfma_f32_16x16x32_bf16 v[112:115], v[192:195], v[200:203], v[112:115]
	v_mfma_f32_16x16x32_bf16 v[100:103], v[180:183], v[208:211], v[100:103]
	v_mfma_f32_16x16x32_bf16 v[96:99], v[192:195], v[208:211], v[96:99]
	v_mfma_f32_16x16x32_bf16 v[84:87], v[180:183], v[216:219], v[84:87]
	v_mfma_f32_16x16x32_bf16 v[80:83], v[192:195], v[216:219], v[80:83]
	v_mfma_f32_16x16x32_bf16 v[68:71], v[180:183], v[224:227], v[68:71]
	v_mfma_f32_16x16x32_bf16 v[64:67], v[192:195], v[224:227], v[64:67]
	s_barrier
; #define PG8_STAGE(bufoff, gbase, voff) do { _Pragma("unroll") for (int _i = 0; _i < 2; ++_i) \
;         __builtin_amdgcn_global_load_lds((const unsigned*)((const char*)(gbase) + (voff)[_i]), (PG8_LAS unsigned*)(lds + (bufoff) + ldsw + _i * 8192), 16, 0, 0); } while (0)
; #define PG8_LDA(dst, b, h) do { _Pragma("unroll") for (int m = 0; m < 4; ++m) _Pragma("unroll") for (int k = 0; k < 2; ++k) dst[m][k] = *(const PG8_LAS bf16x8*)(lds + PG8_SA(b, h) + aoff + m * 2048 + k * 1024); } while (0)
; #define PG8_MMA(ai, bj, At, Bt) do { __builtin_amdgcn_s_setprio(1); _Pragma("unroll") for (int m = 0; m < 4; ++m) _Pragma("unroll") for (int n = 0; n < 2; ++n) _Pragma("unroll") for (int k = 0; k < 2; ++k) \
;         acc[ai][bj][m][n] = __builtin_amdgcn_mfma_f32_16x16x32_bf16(Bt[n][k], At[m][k], acc[ai][bj][m][n], 0, 0, 0); __builtin_amdgcn_s_setprio(0); } while (0)
; #define PG8_WAIT_V(n) asm volatile("s_waitcnt vmcnt(" #n ")" ::: "memory")
; #define PG8_WAIT_L(n) asm volatile("s_waitcnt lgkmcnt(" #n ")" ::: "memory")
; #define PG8_BAR __builtin_amdgcn_s_barrier()
; #define PG8_SCHED __builtin_amdgcn_sched_barrier(0)
; template <class Epi, class Sched, bool ALIGN_EPI = false, bool SP2 = false>
; __device__ __forceinline__ void gemm_phase(PG8_LAS unsigned char* lds, const Gemm g, const Sched& S, const Epi& E) {
;     ...
;             PG8_LDA(At, 1, 1); PG8_STAGE(PG8_SB(1, 0), b3, voffB); PG8_STAGE(PG8_SB(1, 1), b3 + hstep, voffB); PG8_STAGE(PG8_SA(1, 0), a3, voffA);
;             PG8_WAIT_V(8); PG8_WAIT_L(0); PG8_BAR; PG8_MMA(1, 0, At, B0); PG8_MMA(1, 1, At, B1); PG8_BAR; PG8_SCHED;
	s_setprio 0
	s_add_i32 s28, s48, s31
	v_lshl_add_u64 v[160:161], v[160:161], 0, s[10:11]
	s_mov_b32 m0, s28
	ds_read_b128 v[196:199], v175 offset:49152
	ds_read_b128 v[200:203], v175 offset:50176
	ds_read_b128 v[204:207], v175 offset:51200
	ds_read_b128 v[208:211], v175 offset:52224
	ds_read_b128 v[212:215], v175 offset:53248
	ds_read_b128 v[216:219], v175 offset:54272
	ds_read_b128 v[220:223], v175 offset:55296
	ds_read_b128 v[224:227], v175 offset:56320
	global_load_lds_dwordx4 v[160:161], off
	s_add_i32 m0, s28, 0x2000
	s_add_u32 s26, s26, 0x80080
	v_lshl_add_u64 v[160:161], v[184:185], 0, s[10:11]
	s_addc_u32 s27, s27, 0
	s_add_i32 s28, s49, s31
	global_load_lds_dwordx4 v[160:161], off
	v_lshl_add_u64 v[160:161], s[26:27], 0, v[146:147]
	s_mov_b32 m0, s28
	s_nop 0
	global_load_lds_dwordx4 v[160:161], off
	v_lshl_add_u64 v[160:161], s[26:27], 0, v[150:151]
	s_add_i32 m0, s28, 0x2000
	s_nop 0
	global_load_lds_dwordx4 v[160:161], off
	v_lshl_add_u64 v[160:161], v[228:229], 0, s[10:11]
	s_mov_b32 m0, s38
	s_nop 0
	global_load_lds_dwordx4 v[160:161], off
	v_lshl_add_u64 v[160:161], v[230:231], 0, s[10:11]
	s_mov_b32 m0, s39
	s_nop 0
	global_load_lds_dwordx4 v[160:161], off
	s_setprio 1
	s_waitcnt vmcnt(8)
	s_waitcnt lgkmcnt(0)
	s_barrier
	v_mfma_f32_16x16x32_bf16 v[60:63], v[128:131], v[196:199], v[60:63]
	v_mfma_f32_16x16x32_bf16 v[56:59], v[136:139], v[196:199], v[56:59]
	v_mfma_f32_16x16x32_bf16 v[44:47], v[128:131], v[204:207], v[44:47]
	v_mfma_f32_16x16x32_bf16 v[40:43], v[136:139], v[204:207], v[40:43]
	v_mfma_f32_16x16x32_bf16 v[28:31], v[128:131], v[212:215], v[28:31]
	v_mfma_f32_16x16x32_bf16 v[24:27], v[136:139], v[212:215], v[24:27]
	v_mfma_f32_16x16x32_bf16 v[12:15], v[128:131], v[220:223], v[12:15]
	v_mfma_f32_16x16x32_bf16 v[8:11], v[136:139], v[220:223], v[8:11]
	v_mfma_f32_16x16x32_bf16 v[60:63], v[132:135], v[200:203], v[60:63]
	v_mfma_f32_16x16x32_bf16 v[56:59], v[140:143], v[200:203], v[56:59]
	v_mfma_f32_16x16x32_bf16 v[44:47], v[132:135], v[208:211], v[44:47]
	v_mfma_f32_16x16x32_bf16 v[40:43], v[140:143], v[208:211], v[40:43]
	v_mfma_f32_16x16x32_bf16 v[28:31], v[132:135], v[216:219], v[28:31]
	v_mfma_f32_16x16x32_bf16 v[24:27], v[140:143], v[216:219], v[24:27]
	v_mfma_f32_16x16x32_bf16 v[12:15], v[132:135], v[224:227], v[12:15]
	v_mfma_f32_16x16x32_bf16 v[8:11], v[140:143], v[224:227], v[8:11]
	s_setprio 0
	s_setprio 1
	v_mfma_f32_16x16x32_bf16 v[52:55], v[176:179], v[196:199], v[52:55]
	v_mfma_f32_16x16x32_bf16 v[48:51], v[188:191], v[196:199], v[48:51]
	v_mfma_f32_16x16x32_bf16 v[36:39], v[176:179], v[204:207], v[36:39]
	v_mfma_f32_16x16x32_bf16 v[32:35], v[188:191], v[204:207], v[32:35]
	v_mfma_f32_16x16x32_bf16 v[20:23], v[176:179], v[212:215], v[20:23]
	v_mfma_f32_16x16x32_bf16 v[16:19], v[188:191], v[212:215], v[16:19]
	v_mfma_f32_16x16x32_bf16 v[4:7], v[176:179], v[220:223], v[4:7]
	v_mfma_f32_16x16x32_bf16 v[0:3], v[188:191], v[220:223], v[0:3]
	v_mfma_f32_16x16x32_bf16 v[52:55], v[180:183], v[200:203], v[52:55]
	v_mfma_f32_16x16x32_bf16 v[48:51], v[192:195], v[200:203], v[48:51]
	v_mfma_f32_16x16x32_bf16 v[36:39], v[180:183], v[208:211], v[36:39]
	v_mfma_f32_16x16x32_bf16 v[32:35], v[192:195], v[208:211], v[32:35]
	v_mfma_f32_16x16x32_bf16 v[20:23], v[180:183], v[216:219], v[20:23]
	v_mfma_f32_16x16x32_bf16 v[16:19], v[192:195], v[216:219], v[16:19]
	v_mfma_f32_16x16x32_bf16 v[4:7], v[180:183], v[224:227], v[4:7]
	v_mfma_f32_16x16x32_bf16 v[0:3], v[192:195], v[224:227], v[0:3]
	s_barrier
	s_setprio 0
	s_add_i32 s47, s47, 2
	s_add_u32 s24, s24, 0x100
	s_addc_u32 s25, s25, 0
	s_add_u32 s45, s45, 0x100
	s_addc_u32 s46, s46, 0
	s_cmp_gt_u32 s47, 29
	.p2align	6

;     __device__ __forceinline__ bool next(int i, Unit& u) const { if (!base.next(i >> 1, u)) return false; if (i & 1) { u.pm += 64; u.pn += 8; } return true; }
; #define PG8_STAGE(bufoff, gbase, voff) do { _Pragma("unroll") for (int _i = 0; _i < 2; ++_i) \
;         __builtin_amdgcn_global_load_lds((const unsigned*)((const char*)(gbase) + (voff)[_i]), (PG8_LAS unsigned*)(lds + (bufoff) + ldsw + _i * 8192), 16, 0, 0); } while (0)
; #define PG8_LDA(dst, b, h) do { _Pragma("unroll") for (int m = 0; m < 4; ++m) _Pragma("unroll") for (int k = 0; k < 2; ++k) dst[m][k] = *(const PG8_LAS bf16x8*)(lds + PG8_SA(b, h) + aoff + m * 2048 + k * 1024); } while (0)
; #define PG8_LDB(dst, b, h) do { _Pragma("unroll") for (int n = 0; n < 2; ++n) _Pragma("unroll") for (int k = 0; k < 2; ++k) dst[n][k] = *(const PG8_LAS bf16x8*)(lds + PG8_SB(b, h) + boff + n * 2048 + k * 1024); } while (0)
; #define PG8_WAIT_V(n) asm volatile("s_waitcnt vmcnt(" #n ")" ::: "memory")
; #define PG8_WAIT_L(n) asm volatile("s_waitcnt lgkmcnt(" #n ")" ::: "memory")
; #define PG8_BAR __builtin_amdgcn_s_barrier()
; #define PG8_SCHED __builtin_amdgcn_sched_barrier(0)
; template <class Epi, class Sched, bool ALIGN_EPI = false, bool SP2 = false>
; __device__ __forceinline__ void gemm_phase(PG8_LAS unsigned char* lds, const Gemm g, const Sched& S, const Epi& E) {
;     ...
;         const bool has_next = S.next(ui + 1, nxt);
;         const char* nA = has_next ? (const char*)g.A + (size_t)nxt.pm * tstep : cA; const char* nB = has_next ? (const char*)g.Bt + (size_t)nxt.pn * tstep : cB;
;         for (int t = 0; t < nt; t += 2) {
;             const bool last = (t == nt - 2);
;             const char* a1 = cA + (size_t)(t + 1) * kstep;
;             const char* a2 = last ? nA : cA + (size_t)(t + 2) * kstep; const char* b2 = last ? nB : cB + (size_t)(t + 2) * kstep;
;             const char* a3 = a2 + kstep; const char* b3 = b2 + kstep;
;             if (last && has_next) S.a_ready(nxt);
;             if constexpr (SP2) {
;             PG8_LDB(B0, 0, 0); PG8_LDB(B1, 0, 1); PG8_SCHED; PG8_LDA(At, 0, 0); PG8_STAGE(PG8_SA(1, 1), a1 + hstep, voffA);
;             PG8_WAIT_V(8); PG8_WAIT_L(0); PG8_BAR; PG8_MMA(0, 0, At, B0); PG8_MMA(0, 1, At, B1); PG8_BAR; PG8_SCHED;
;             PG8_LDA(At, 0, 1); PG8_STAGE(PG8_SB(0, 0), b2, voffB); PG8_STAGE(PG8_SB(0, 1), b2 + hstep, voffB); PG8_STAGE(PG8_SA(0, 0), a2, voffA);
.LBB0_1070:
	s_ashr_i32 s19, s18, 31
	s_lshl_b64 s[20:21], s[18:19], 22
	s_add_u32 s20, s72, s20
	s_addc_u32 s21, s73, s21
	s_and_b64 s[22:23], s[0:1], exec
	s_cselect_b32 s19, s21, s27
	s_cselect_b32 s51, s20, s26
	s_ashr_i32 s17, s16, 31
	s_lshl_b64 s[22:23], s[16:17], 22
	v_readlane_b32 s30, v236, 54
	v_readlane_b32 s31, v236, 55
	s_add_u32 s22, s30, s22
	s_addc_u32 s23, s31, s23
	s_and_b64 s[30:31], s[0:1], exec
	s_cselect_b32 s17, s23, s29
	s_cselect_b32 s52, s22, s28
	s_add_u32 s26, s26, 0x200080
	s_addc_u32 s27, s27, 0
	s_add_u32 s53, s28, 0x100
	s_addc_u32 s54, s29, 0
	s_mov_b32 s55, -2
	ds_read_b128 v[64:67], v165
	ds_read_b128 v[108:111], v165 offset:1024
	ds_read_b128 v[116:119], v165 offset:2048
	ds_read_b128 v[128:131], v165 offset:3072
	ds_read_b128 v[156:159], v166
	ds_read_b128 v[168:171], v166 offset:1024
	ds_read_b128 v[172:175], v166 offset:2048
	ds_read_b128 v[176:179], v166 offset:3072
	s_add_u32 s28, s26, 0xffe00080
	s_addc_u32 s29, s27, -1
	s_cmpk_eq_i32 s55, 0x7c
	s_cselect_b32 s31, s19, s29
	s_cselect_b32 s30, s51, s28
	s_cselect_b32 s29, s17, s54
	s_cselect_b32 s28, s52, s53
	v_lshl_add_u64 v[160:161], s[26:27], 0, v[148:149]
	s_add_i32 m0, s35, 0xc000
	ds_read_b128 v[180:183], v167
	ds_read_b128 v[184:187], v167 offset:1024
	ds_read_b128 v[188:191], v167 offset:2048
	ds_read_b128 v[192:195], v167 offset:3072
	ds_read_b128 v[196:199], v167 offset:4096
	ds_read_b128 v[200:203], v167 offset:5120
	ds_read_b128 v[204:207], v167 offset:6144
	ds_read_b128 v[208:211], v167 offset:7168
	global_load_lds_dwordx4 v[160:161], off
	v_lshl_add_u64 v[160:161], s[26:27], 0, v[150:151]
	s_add_i32 m0, s35, 0xe000
	s_nop 0
	global_load_lds_dwordx4 v[160:161], off
	s_setprio 1
	s_waitcnt vmcnt(8)
	s_waitcnt lgkmcnt(0)
	s_barrier
	v_mfma_f32_16x16x32_bf16 v[140:143], v[64:67], v[180:183], 0
	v_mfma_f32_16x16x32_bf16 v[136:139], v[116:119], v[180:183], 0
	v_mfma_f32_16x16x32_bf16 v[120:123], v[64:67], v[188:191], 0
	v_mfma_f32_16x16x32_bf16 v[112:115], v[116:119], v[188:191], 0
	v_mfma_f32_16x16x32_bf16 v[96:99], v[64:67], v[196:199], 0
	v_mfma_f32_16x16x32_bf16 v[92:95], v[116:119], v[196:199], 0
	v_mfma_f32_16x16x32_bf16 v[80:83], v[64:67], v[204:207], 0
	v_mfma_f32_16x16x32_bf16 v[76:79], v[116:119], v[204:207], 0
	v_mfma_f32_16x16x32_bf16 v[140:143], v[108:111], v[184:187], v[140:143]
	v_mfma_f32_16x16x32_bf16 v[136:139], v[128:131], v[184:187], v[136:139]
	v_mfma_f32_16x16x32_bf16 v[120:123], v[108:111], v[192:195], v[120:123]
	v_mfma_f32_16x16x32_bf16 v[112:115], v[128:131], v[192:195], v[112:115]
	v_mfma_f32_16x16x32_bf16 v[96:99], v[108:111], v[200:203], v[96:99]
	v_mfma_f32_16x16x32_bf16 v[92:95], v[128:131], v[200:203], v[92:95]
	v_mfma_f32_16x16x32_bf16 v[80:83], v[108:111], v[208:211], v[80:83]
	v_mfma_f32_16x16x32_bf16 v[76:79], v[128:131], v[208:211], v[76:79]
	s_setprio 0
	s_setprio 1
	v_mfma_f32_16x16x32_bf16 v[132:135], v[156:159], v[180:183], 0
	v_mfma_f32_16x16x32_bf16 v[124:127], v[172:175], v[180:183], 0
	v_mfma_f32_16x16x32_bf16 v[104:107], v[156:159], v[188:191], 0
	v_mfma_f32_16x16x32_bf16 v[100:103], v[172:175], v[188:191], 0
	v_mfma_f32_16x16x32_bf16 v[88:91], v[156:159], v[196:199], 0
	v_mfma_f32_16x16x32_bf16 v[84:87], v[172:175], v[196:199], 0
	v_mfma_f32_16x16x32_bf16 v[72:75], v[156:159], v[204:207], 0
	v_mfma_f32_16x16x32_bf16 v[68:71], v[172:175], v[204:207], 0
	v_mfma_f32_16x16x32_bf16 v[132:135], v[168:171], v[184:187], v[132:135]
	v_mfma_f32_16x16x32_bf16 v[124:127], v[176:179], v[184:187], v[124:127]
	v_mfma_f32_16x16x32_bf16 v[104:107], v[168:171], v[192:195], v[104:107]
	v_mfma_f32_16x16x32_bf16 v[100:103], v[176:179], v[192:195], v[100:103]
	v_mfma_f32_16x16x32_bf16 v[88:91], v[168:171], v[200:203], v[88:91]
	v_mfma_f32_16x16x32_bf16 v[84:87], v[176:179], v[200:203], v[84:87]
	v_mfma_f32_16x16x32_bf16 v[72:75], v[168:171], v[208:211], v[72:75]
	v_mfma_f32_16x16x32_bf16 v[68:71], v[176:179], v[208:211], v[68:71]
	s_barrier
	s_setprio 0
	s_add_i32 s56, s45, s34
	v_lshl_add_u64 v[160:161], s[28:29], 0, v[144:145]
	s_mov_b32 m0, s56
	ds_read_b128 v[180:183], v167 offset:16384
	ds_read_b128 v[184:187], v167 offset:17408
	ds_read_b128 v[188:191], v167 offset:18432
	ds_read_b128 v[192:195], v167 offset:19456
	ds_read_b128 v[196:199], v167 offset:20480
	ds_read_b128 v[200:203], v167 offset:21504
	ds_read_b128 v[204:207], v167 offset:22528
	ds_read_b128 v[208:211], v167 offset:23552
	global_load_lds_dwordx4 v[160:161], off
	s_add_i32 m0, s56, 0x2000
	s_add_u32 s56, s28, 0x200000
	v_lshl_add_u64 v[212:213], s[28:29], 0, v[146:147]
	s_addc_u32 s57, s29, 0
	s_add_i32 s58, s46, s34
	global_load_lds_dwordx4 v[212:213], off
	v_lshl_add_u64 v[214:215], s[56:57], 0, v[144:145]
	s_mov_b32 m0, s58
	v_lshl_add_u64 v[216:217], s[30:31], 0, v[146:147]
	global_load_lds_dwordx4 v[214:215], off
	v_lshl_add_u64 v[214:215], s[56:57], 0, v[146:147]
	s_add_i32 m0, s58, 0x2000
	s_nop 0
	global_load_lds_dwordx4 v[214:215], off
	v_lshl_add_u64 v[214:215], s[30:31], 0, v[144:145]
	s_mov_b32 m0, s35
	s_nop 0
	global_load_lds_dwordx4 v[214:215], off
	s_mov_b32 m0, s36
	s_nop 0
	global_load_lds_dwordx4 v[216:217], off
	s_setprio 1
	s_waitcnt vmcnt(8)
	s_waitcnt lgkmcnt(0)
	s_barrier
; #define PG8_STAGE(bufoff, gbase, voff) do { _Pragma("unroll") for (int _i = 0; _i < 2; ++_i) \
;         __builtin_amdgcn_global_load_lds((const unsigned*)((const char*)(gbase) + (voff)[_i]), (PG8_LAS unsigned*)(lds + (bufoff) + ldsw + _i * 8192), 16, 0, 0); } while (0)
; #define PG8_LDA(dst, b, h) do { _Pragma("unroll") for (int m = 0; m < 4; ++m) _Pragma("unroll") for (int k = 0; k < 2; ++k) dst[m][k] = *(const PG8_LAS bf16x8*)(lds + PG8_SA(b, h) + aoff + m * 2048 + k * 1024); } while (0)
; #define PG8_LDB(dst, b, h) do { _Pragma("unroll") for (int n = 0; n < 2; ++n) _Pragma("unroll") for (int k = 0; k < 2; ++k) dst[n][k] = *(const PG8_LAS bf16x8*)(lds + PG8_SB(b, h) + boff + n * 2048 + k * 1024); } while (0)
; #define PG8_MMA(ai, bj, At, Bt) do { __builtin_amdgcn_s_setprio(1); _Pragma("unroll") for (int m = 0; m < 4; ++m) _Pragma("unroll") for (int n = 0; n < 2; ++n) _Pragma("unroll") for (int k = 0; k < 2; ++k) \
;         acc[ai][bj][m][n] = __builtin_amdgcn_mfma_f32_16x16x32_bf16(Bt[n][k], At[m][k], acc[ai][bj][m][n], 0, 0, 0); __builtin_amdgcn_s_setprio(0); } while (0)
; #define PG8_WAIT_V(n) asm volatile("s_waitcnt vmcnt(" #n ")" ::: "memory")
; #define PG8_WAIT_L(n) asm volatile("s_waitcnt lgkmcnt(" #n ")" ::: "memory")
; #define PG8_BAR __builtin_amdgcn_s_barrier()
; #define PG8_SCHED __builtin_amdgcn_sched_barrier(0)
; template <class Epi, class Sched, bool ALIGN_EPI = false, bool SP2 = false>
; __device__ __forceinline__ void gemm_phase(PG8_LAS unsigned char* lds, const Gemm g, const Sched& S, const Epi& E) {
;     ...
;             PG8_WAIT_V(8); PG8_WAIT_L(0); PG8_BAR; PG8_MMA(1, 0, At, B0); PG8_MMA(1, 1, At, B1); PG8_BAR; PG8_SCHED;
;             PG8_LDB(B0, 1, 0); PG8_LDB(B1, 1, 1); PG8_SCHED; PG8_LDA(At, 1, 0); PG8_STAGE(PG8_SA(0, 1), a2 + hstep, voffA);
;             PG8_WAIT_V(8); PG8_WAIT_L(0); PG8_BAR; PG8_MMA(0, 0, At, B0); PG8_MMA(0, 1, At, B1); PG8_BAR; PG8_SCHED;
;             PG8_LDA(At, 1, 1); PG8_STAGE(PG8_SB(1, 0), b3, voffB); PG8_STAGE(PG8_SB(1, 1), b3 + hstep, voffB); PG8_STAGE(PG8_SA(1, 0), a3, voffA);
	v_mfma_f32_16x16x32_bf16 v[60:63], v[64:67], v[180:183], 0
	v_mfma_f32_16x16x32_bf16 v[56:59], v[116:119], v[180:183], 0
	v_mfma_f32_16x16x32_bf16 v[44:47], v[64:67], v[188:191], 0
	v_mfma_f32_16x16x32_bf16 v[40:43], v[116:119], v[188:191], 0
	v_mfma_f32_16x16x32_bf16 v[28:31], v[64:67], v[196:199], 0
	v_mfma_f32_16x16x32_bf16 v[24:27], v[116:119], v[196:199], 0
	v_mfma_f32_16x16x32_bf16 v[12:15], v[64:67], v[204:207], 0
	v_mfma_f32_16x16x32_bf16 v[8:11], v[116:119], v[204:207], 0
	v_mfma_f32_16x16x32_bf16 v[60:63], v[108:111], v[184:187], v[60:63]
	v_mfma_f32_16x16x32_bf16 v[56:59], v[128:131], v[184:187], v[56:59]
	v_mfma_f32_16x16x32_bf16 v[44:47], v[108:111], v[192:195], v[44:47]
	v_mfma_f32_16x16x32_bf16 v[40:43], v[128:131], v[192:195], v[40:43]
	v_mfma_f32_16x16x32_bf16 v[28:31], v[108:111], v[200:203], v[28:31]
	v_mfma_f32_16x16x32_bf16 v[24:27], v[128:131], v[200:203], v[24:27]
	v_mfma_f32_16x16x32_bf16 v[12:15], v[108:111], v[208:211], v[12:15]
	v_mfma_f32_16x16x32_bf16 v[8:11], v[128:131], v[208:211], v[8:11]
	s_setprio 0
	s_setprio 1
	v_mfma_f32_16x16x32_bf16 v[52:55], v[156:159], v[180:183], 0
	v_mfma_f32_16x16x32_bf16 v[48:51], v[172:175], v[180:183], 0
	v_mfma_f32_16x16x32_bf16 v[36:39], v[156:159], v[188:191], 0
	v_mfma_f32_16x16x32_bf16 v[32:35], v[172:175], v[188:191], 0
	v_mfma_f32_16x16x32_bf16 v[20:23], v[156:159], v[196:199], 0
	v_mfma_f32_16x16x32_bf16 v[16:19], v[172:175], v[196:199], 0
	v_mfma_f32_16x16x32_bf16 v[4:7], v[156:159], v[204:207], 0
	v_mfma_f32_16x16x32_bf16 v[0:3], v[172:175], v[204:207], 0
	v_mfma_f32_16x16x32_bf16 v[52:55], v[168:171], v[184:187], v[52:55]
	v_mfma_f32_16x16x32_bf16 v[48:51], v[176:179], v[184:187], v[48:51]
	v_mfma_f32_16x16x32_bf16 v[36:39], v[168:171], v[192:195], v[36:39]
	v_mfma_f32_16x16x32_bf16 v[32:35], v[176:179], v[192:195], v[32:35]
	v_mfma_f32_16x16x32_bf16 v[20:23], v[168:171], v[200:203], v[20:23]
	v_mfma_f32_16x16x32_bf16 v[16:19], v[176:179], v[200:203], v[16:19]
	v_mfma_f32_16x16x32_bf16 v[4:7], v[168:171], v[208:211], v[4:7]
	v_mfma_f32_16x16x32_bf16 v[0:3], v[176:179], v[208:211], v[0:3]
	s_barrier
	s_setprio 0
	s_add_i32 s56, 0, 0x18000
	s_add_i32 s57, 0, 0x1c000
	v_add_u32_e32 v128, s56, v163
	v_add_u32_e32 v176, s57, v163
	ds_read_b128 v[64:67], v128
	ds_read_b128 v[108:111], v128 offset:1024
	ds_read_b128 v[116:119], v128 offset:2048
	ds_read_b128 v[128:131], v128 offset:3072
	ds_read_b128 v[156:159], v176
	ds_read_b128 v[168:171], v176 offset:1024
	ds_read_b128 v[172:175], v176 offset:2048
	ds_read_b128 v[176:179], v176 offset:3072
	s_add_u32 s30, s30, 0x200000
	s_addc_u32 s31, s31, 0
	s_mov_b32 m0, s37
	v_lshl_add_u64 v[218:219], s[30:31], 0, v[144:145]
	ds_read_b128 v[180:183], v167 offset:32768
	ds_read_b128 v[184:187], v167 offset:33792
	ds_read_b128 v[188:191], v167 offset:34816
	ds_read_b128 v[192:195], v167 offset:35840
	ds_read_b128 v[196:199], v167 offset:36864
	ds_read_b128 v[200:203], v167 offset:37888
	ds_read_b128 v[204:207], v167 offset:38912
	ds_read_b128 v[208:211], v167 offset:39936
	global_load_lds_dwordx4 v[218:219], off
	v_lshl_add_u64 v[218:219], s[30:31], 0, v[146:147]
	s_mov_b32 m0, s38
	s_nop 0
	global_load_lds_dwordx4 v[218:219], off
	s_setprio 1
	s_waitcnt vmcnt(8)
	s_waitcnt lgkmcnt(0)
	s_barrier
	v_mfma_f32_16x16x32_bf16 v[140:143], v[64:67], v[180:183], v[140:143]
	v_mfma_f32_16x16x32_bf16 v[136:139], v[116:119], v[180:183], v[136:139]
	v_mfma_f32_16x16x32_bf16 v[120:123], v[64:67], v[188:191], v[120:123]
	v_mfma_f32_16x16x32_bf16 v[112:115], v[116:119], v[188:191], v[112:115]
	v_mfma_f32_16x16x32_bf16 v[96:99], v[64:67], v[196:199], v[96:99]
	v_mfma_f32_16x16x32_bf16 v[92:95], v[116:119], v[196:199], v[92:95]
	v_mfma_f32_16x16x32_bf16 v[80:83], v[64:67], v[204:207], v[80:83]
	v_mfma_f32_16x16x32_bf16 v[76:79], v[116:119], v[204:207], v[76:79]
	v_mfma_f32_16x16x32_bf16 v[140:143], v[108:111], v[184:187], v[140:143]
	v_mfma_f32_16x16x32_bf16 v[136:139], v[128:131], v[184:187], v[136:139]
	v_mfma_f32_16x16x32_bf16 v[120:123], v[108:111], v[192:195], v[120:123]
	v_mfma_f32_16x16x32_bf16 v[112:115], v[128:131], v[192:195], v[112:115]
	v_mfma_f32_16x16x32_bf16 v[96:99], v[108:111], v[200:203], v[96:99]
	v_mfma_f32_16x16x32_bf16 v[92:95], v[128:131], v[200:203], v[92:95]
	v_mfma_f32_16x16x32_bf16 v[80:83], v[108:111], v[208:211], v[80:83]
	v_mfma_f32_16x16x32_bf16 v[76:79], v[128:131], v[208:211], v[76:79]
	s_setprio 0
	s_setprio 1
	v_mfma_f32_16x16x32_bf16 v[132:135], v[156:159], v[180:183], v[132:135]
	v_mfma_f32_16x16x32_bf16 v[124:127], v[172:175], v[180:183], v[124:127]
	v_mfma_f32_16x16x32_bf16 v[104:107], v[156:159], v[188:191], v[104:107]
	v_mfma_f32_16x16x32_bf16 v[100:103], v[172:175], v[188:191], v[100:103]
	v_mfma_f32_16x16x32_bf16 v[88:91], v[156:159], v[196:199], v[88:91]
	v_mfma_f32_16x16x32_bf16 v[84:87], v[172:175], v[196:199], v[84:87]
	v_mfma_f32_16x16x32_bf16 v[72:75], v[156:159], v[204:207], v[72:75]
	v_mfma_f32_16x16x32_bf16 v[68:71], v[172:175], v[204:207], v[68:71]
	v_mfma_f32_16x16x32_bf16 v[132:135], v[168:171], v[184:187], v[132:135]
	v_mfma_f32_16x16x32_bf16 v[124:127], v[176:179], v[184:187], v[124:127]
	v_mfma_f32_16x16x32_bf16 v[104:107], v[168:171], v[192:195], v[104:107]
	v_mfma_f32_16x16x32_bf16 v[100:103], v[176:179], v[192:195], v[100:103]
	v_mfma_f32_16x16x32_bf16 v[88:91], v[168:171], v[200:203], v[88:91]
	v_mfma_f32_16x16x32_bf16 v[84:87], v[176:179], v[200:203], v[84:87]
	v_mfma_f32_16x16x32_bf16 v[72:75], v[168:171], v[208:211], v[72:75]
	v_mfma_f32_16x16x32_bf16 v[68:71], v[176:179], v[208:211], v[68:71]
	s_barrier
; #define PG8_STAGE(bufoff, gbase, voff) do { _Pragma("unroll") for (int _i = 0; _i < 2; ++_i) \
;         __builtin_amdgcn_global_load_lds((const unsigned*)((const char*)(gbase) + (voff)[_i]), (PG8_LAS unsigned*)(lds + (bufoff) + ldsw + _i * 8192), 16, 0, 0); } while (0)
; #define PG8_LDA(dst, b, h) do { _Pragma("unroll") for (int m = 0; m < 4; ++m) _Pragma("unroll") for (int k = 0; k < 2; ++k) dst[m][k] = *(const PG8_LAS bf16x8*)(lds + PG8_SA(b, h) + aoff + m * 2048 + k * 1024); } while (0)
; #define PG8_MMA(ai, bj, At, Bt) do { __builtin_amdgcn_s_setprio(1); _Pragma("unroll") for (int m = 0; m < 4; ++m) _Pragma("unroll") for (int n = 0; n < 2; ++n) _Pragma("unroll") for (int k = 0; k < 2; ++k) \
;         acc[ai][bj][m][n] = __builtin_amdgcn_mfma_f32_16x16x32_bf16(Bt[n][k], At[m][k], acc[ai][bj][m][n], 0, 0, 0); __builtin_amdgcn_s_setprio(0); } while (0)
; #define PG8_WAIT_V(n) asm volatile("s_waitcnt vmcnt(" #n ")" ::: "memory")
; #define PG8_WAIT_L(n) asm volatile("s_waitcnt lgkmcnt(" #n ")" ::: "memory")
; #define PG8_BAR __builtin_amdgcn_s_barrier()
; #define PG8_SCHED __builtin_amdgcn_sched_barrier(0)
; template <class Epi, class Sched, bool ALIGN_EPI = false, bool SP2 = false>
; __device__ __forceinline__ void gemm_phase(PG8_LAS unsigned char* lds, const Gemm g, const Sched& S, const Epi& E) {
;     ...
;             PG8_LDA(At, 1, 1); PG8_STAGE(PG8_SB(1, 0), b3, voffB); PG8_STAGE(PG8_SB(1, 1), b3 + hstep, voffB); PG8_STAGE(PG8_SA(1, 0), a3, voffA);
;             PG8_WAIT_V(8); PG8_WAIT_L(0); PG8_BAR; PG8_MMA(1, 0, At, B0); PG8_MMA(1, 1, At, B1); PG8_BAR; PG8_SCHED;
	s_setprio 0
	s_add_i32 s30, s56, s34
	v_lshl_add_u64 v[160:161], v[160:161], 0, s[4:5]
	s_mov_b32 m0, s30
	ds_read_b128 v[180:183], v167 offset:49152
	ds_read_b128 v[184:187], v167 offset:50176
	ds_read_b128 v[188:191], v167 offset:51200
	ds_read_b128 v[192:195], v167 offset:52224
	ds_read_b128 v[196:199], v167 offset:53248
	ds_read_b128 v[200:203], v167 offset:54272
	ds_read_b128 v[204:207], v167 offset:55296
	ds_read_b128 v[208:211], v167 offset:56320
	global_load_lds_dwordx4 v[160:161], off
	s_add_i32 m0, s30, 0x2000
	s_add_u32 s28, s28, 0x200080
	v_lshl_add_u64 v[160:161], v[212:213], 0, s[4:5]
	s_addc_u32 s29, s29, 0
	s_add_i32 s30, s57, s34
	global_load_lds_dwordx4 v[160:161], off
	v_lshl_add_u64 v[160:161], s[28:29], 0, v[144:145]
	s_mov_b32 m0, s30
	s_nop 0
	global_load_lds_dwordx4 v[160:161], off
	v_lshl_add_u64 v[160:161], s[28:29], 0, v[146:147]
	s_add_i32 m0, s30, 0x2000
	s_nop 0
	global_load_lds_dwordx4 v[160:161], off
	v_lshl_add_u64 v[160:161], v[214:215], 0, s[4:5]
	s_mov_b32 m0, s42
	s_nop 0
	global_load_lds_dwordx4 v[160:161], off
	v_lshl_add_u64 v[160:161], v[216:217], 0, s[4:5]
	s_mov_b32 m0, s43
	s_nop 0
	global_load_lds_dwordx4 v[160:161], off
	s_setprio 1
	s_waitcnt vmcnt(8)
	s_waitcnt lgkmcnt(0)
	s_barrier
	v_mfma_f32_16x16x32_bf16 v[60:63], v[64:67], v[180:183], v[60:63]
	v_mfma_f32_16x16x32_bf16 v[56:59], v[116:119], v[180:183], v[56:59]
	v_mfma_f32_16x16x32_bf16 v[44:47], v[64:67], v[188:191], v[44:47]
	v_mfma_f32_16x16x32_bf16 v[40:43], v[116:119], v[188:191], v[40:43]
	v_mfma_f32_16x16x32_bf16 v[28:31], v[64:67], v[196:199], v[28:31]
	v_mfma_f32_16x16x32_bf16 v[24:27], v[116:119], v[196:199], v[24:27]
	v_mfma_f32_16x16x32_bf16 v[12:15], v[64:67], v[204:207], v[12:15]
	v_mfma_f32_16x16x32_bf16 v[8:11], v[116:119], v[204:207], v[8:11]
	v_mfma_f32_16x16x32_bf16 v[60:63], v[108:111], v[184:187], v[60:63]
	v_mfma_f32_16x16x32_bf16 v[56:59], v[128:131], v[184:187], v[56:59]
	v_mfma_f32_16x16x32_bf16 v[44:47], v[108:111], v[192:195], v[44:47]
	v_mfma_f32_16x16x32_bf16 v[40:43], v[128:131], v[192:195], v[40:43]
	v_mfma_f32_16x16x32_bf16 v[28:31], v[108:111], v[200:203], v[28:31]
	v_mfma_f32_16x16x32_bf16 v[24:27], v[128:131], v[200:203], v[24:27]
	v_mfma_f32_16x16x32_bf16 v[12:15], v[108:111], v[208:211], v[12:15]
	v_mfma_f32_16x16x32_bf16 v[8:11], v[128:131], v[208:211], v[8:11]
	s_setprio 0
	s_setprio 1
	v_mfma_f32_16x16x32_bf16 v[52:55], v[156:159], v[180:183], v[52:55]
	v_mfma_f32_16x16x32_bf16 v[48:51], v[172:175], v[180:183], v[48:51]
	v_mfma_f32_16x16x32_bf16 v[36:39], v[156:159], v[188:191], v[36:39]
	v_mfma_f32_16x16x32_bf16 v[32:35], v[172:175], v[188:191], v[32:35]
	v_mfma_f32_16x16x32_bf16 v[20:23], v[156:159], v[196:199], v[20:23]
	v_mfma_f32_16x16x32_bf16 v[16:19], v[172:175], v[196:199], v[16:19]
	v_mfma_f32_16x16x32_bf16 v[4:7], v[156:159], v[204:207], v[4:7]
	v_mfma_f32_16x16x32_bf16 v[0:3], v[172:175], v[204:207], v[0:3]
	v_mfma_f32_16x16x32_bf16 v[52:55], v[168:171], v[184:187], v[52:55]
	v_mfma_f32_16x16x32_bf16 v[48:51], v[176:179], v[184:187], v[48:51]
	v_mfma_f32_16x16x32_bf16 v[36:39], v[168:171], v[192:195], v[36:39]
	v_mfma_f32_16x16x32_bf16 v[32:35], v[176:179], v[192:195], v[32:35]
	v_mfma_f32_16x16x32_bf16 v[20:23], v[168:171], v[200:203], v[20:23]
	v_mfma_f32_16x16x32_bf16 v[16:19], v[176:179], v[200:203], v[16:19]
	v_mfma_f32_16x16x32_bf16 v[4:7], v[168:171], v[208:211], v[4:7]
	v_mfma_f32_16x16x32_bf16 v[0:3], v[176:179], v[208:211], v[0:3]
	s_barrier
	s_setprio 0
	s_add_i32 s55, s55, 2
	s_add_u32 s26, s26, 0x100
	s_addc_u32 s27, s27, 0
	s_add_u32 s53, s53, 0x100
	s_addc_u32 s54, s54, 0
	s_cmpk_gt_u32 s55, 0x7d
	.p2align	6
